# v20: v17 + P11 joint reduction: both tokens of a sub-tile reduced with one permlane32 swap and stored by one full-wave store (fewer VALU/exec toggles)
# speedup vs baseline: 1.0059x; 1.0037x over previous
; #define LAS __attribute__((address_space(3)))
; DI size_t sc_row_off(int b, int s) { const int qb = s >> 7; return ((size_t)(b * 2080 + ((qb * (qb + 1)) >> 1))) * 16384 + (size_t)(s & 127) * ((qb + 1) * 128); }
; DI void indexer_phase(const unsigned short* QI, const unsigned short* KI16, const float* WI, float* SC, LAS unsigned char* lds, int tid, int bid, int G) {
;     ...
;             float* sc0 = SC + sc_row_off(b, tb + 2 * w); float* sc1 = SC + sc_row_off(b, tb + 2 * w + 1);
;             const unsigned short* src = KI16 + (size_t)b * SEQ * 128 + (size_t)key0 * 128 + ch * 8;
;             u32x4 a0, a1, b0 = {0u, 0u, 0u, 0u}, b1 = {0u, 0u, 0u, 0u};
;             a0 = *(const u32x4*)src; a1 = *(const u32x4*)(src + 32 * 128);
;             if (nt > 1) { b0 = *(const u32x4*)(src + 64 * 128); b1 = *(const u32x4*)(src + 96 * 128); }
;             __syncthreads();
;             *(LAS u32x4*)(buf0 + key0 * KT_ROWB + ch * 16) = a0; *(LAS u32x4*)(buf0 + (key0 + 32) * KT_ROWB + ch * 16) = a1;
;             __syncthreads();
.LBB0_1822:
	s_add_i32 s6, s43, s36
	s_ashr_i32 s7, s6, 7
	s_add_i32 s8, s7, 1
	s_mul_i32 s7, s8, s7
	s_and_b32 s9, s6, 0x7e
	s_ashr_i32 s10, s7, 1
	s_lshl_b32 s8, s8, 7
	s_or_b32 s11, s9, 1
	s_cmp_gt_i32 s41, -1
	s_mul_hi_i32 s7, s8, s9
	s_mul_i32 s6, s8, s9
	s_mul_hi_i32 s9, s8, s11
	s_mul_i32 s8, s8, s11
	s_cselect_b64 s[14:15], -1, 0
	s_cmp_lt_i32 s41, 0
	s_barrier
	s_waitcnt vmcnt(1)
	ds_write_b128 v209, v[132:135]
	s_waitcnt vmcnt(0)
	ds_write_b128 v209, v[136:139] offset:8704
	s_waitcnt lgkmcnt(0)
	s_barrier
	s_cbranch_scc1 .LBB0_1843
	s_ashr_i32 s11, s10, 31
	s_lshl_b64 s[18:19], s[10:11], 16
	s_add_u32 s11, s17, s18
	s_addc_u32 s22, s33, s19
	s_lshl_b64 s[18:19], s[6:7], 2
	s_add_u32 s18, s11, s18
	s_addc_u32 s19, s22, s19
	s_lshl_b64 s[20:21], s[8:9], 2
	s_add_u32 s20, s11, s20
	s_addc_u32 s21, s22, s21
	s_mov_b32 s11, 3
	v_mov_b32_e32 v32, v206
	v_mov_b64_e32 v[34:35], v[200:201]
	s_sub_u32 s98, s20, s18
	v_mov_b32_e32 v248, s98
	s_nop 0
	v_cndmask_b32_e64 v248, v248, 0, s[4:5]
	s_branch .LBB0_1825

; #define LAS __attribute__((address_space(3)))
; DI void indexer_tile(const LAS unsigned char* buf, const f16x8 (&af)[2][8], const f32x4 (&wv)[2][4], float* sc0, float* sc1, int kt, int r32, int h2) {
;     typedef float f32x2_t __attribute__((ext_vector_type(2)));
;     f16x8 bfr[2][8];
; #pragma unroll
;     for (int sub = 0; sub < 2; ++sub)
; #pragma unroll
;         for (int ks = 0; ks < 8; ++ks) bfr[sub][ks] = *(const LAS f16x8*)(buf + (32 * sub + r32) * KT_ROWB + (16 * ks + 8 * h2) * 2);
;     __builtin_amdgcn_sched_barrier(0);
; #pragma unroll
;     for (int sub = 0; sub < 2; ++sub) {
;         f32x16 c0, c1;
; #pragma unroll
;         for (int i = 0; i < 16; ++i) { c0[i] = 0.f; c1[i] = 0.f; }
; #pragma unroll
;         for (int ks = 0; ks < 8; ++ks) { c0 = __builtin_amdgcn_mfma_f32_32x32x16_f16(af[0][ks], bfr[sub][ks], c0, 0, 0, 0); c1 = __builtin_amdgcn_mfma_f32_32x32x16_f16(af[1][ks], bfr[sub][ks], c1, 0, 0, 0); }
;         f32x2_t a0 = {0.f, 0.f}, a1 = {0.f, 0.f};
; #pragma unroll
;         for (int q = 0; q < 4; ++q)
; #pragma unroll
;             for (int e = 0; e < 4; e += 2) {
;                 const f32x2_t r0 = {relu1(c0[4 * q + e]), relu1(c0[4 * q + e + 1])};
;                 const f32x2_t r1 = {relu1(c1[4 * q + e]), relu1(c1[4 * q + e + 1])};
;                 const f32x2_t w0 = {wv[0][q][e], wv[0][q][e + 1]}, w1 = {wv[1][q][e], wv[1][q][e + 1]};
;                 a0 = __builtin_elementwise_fma(r0, w0, a0); a1 = __builtin_elementwise_fma(r1, w1, a1); }
;         float s0 = a0.x + a0.y, s1 = a1.x + a1.y;
;         s0 += __shfl_xor(s0, 32); s1 += __shfl_xor(s1, 32);
;         if (h2 == 0) { sc0[kt * 64 + 32 * sub + r32] = s0; sc1[kt * 64 + 32 * sub + r32] = s1; }
.LBB0_1827:
	ds_read_b128 v[0:3], v207
	ds_read_b128 v[210:213], v207 offset:32
	ds_read_b128 v[214:217], v207 offset:64
	ds_read_b128 v[218:221], v207 offset:96
	ds_read_b128 v[222:225], v207 offset:128
	ds_read_b128 v[226:229], v207 offset:160
	ds_read_b128 v[230:233], v207 offset:192
	ds_read_b128 v[234:237], v207 offset:224
	ds_read_b128 v[176:179], v207 offset:8704
	ds_read_b128 v[172:175], v207 offset:8736
	ds_read_b128 v[168:171], v207 offset:8768
	ds_read_b128 v[164:167], v207 offset:8800
	ds_read_b128 v[160:163], v207 offset:8832
	ds_read_b128 v[156:159], v207 offset:8864
	ds_read_b128 v[152:155], v207 offset:8896
	ds_read_b128 v[148:151], v207 offset:8928
	s_waitcnt lgkmcnt(15)
	v_mfma_f32_32x32x16_f16 v[16:31], v[36:39], v[0:3], 0
	s_waitcnt lgkmcnt(14)
	v_mfma_f32_32x32x16_f16 v[16:31], v[40:43], v[210:213], v[16:31]
	s_waitcnt lgkmcnt(13)
	v_mfma_f32_32x32x16_f16 v[16:31], v[44:47], v[214:217], v[16:31]
	s_waitcnt lgkmcnt(12)
	v_mfma_f32_32x32x16_f16 v[16:31], v[48:51], v[218:221], v[16:31]
	s_waitcnt lgkmcnt(11)
	v_mfma_f32_32x32x16_f16 v[16:31], v[52:55], v[222:225], v[16:31]
	s_waitcnt lgkmcnt(10)
	v_mfma_f32_32x32x16_f16 v[16:31], v[56:59], v[226:229], v[16:31]
	s_waitcnt lgkmcnt(9)
	v_mfma_f32_32x32x16_f16 v[16:31], v[60:63], v[230:233], v[16:31]
	s_waitcnt lgkmcnt(8)
	v_mfma_f32_32x32x16_f16 v[16:31], v[64:67], v[234:237], v[16:31]
	v_mfma_f32_32x32x16_f16 v[0:15], v[84:87], v[0:3], 0
	v_mfma_f32_32x32x16_f16 v[0:15], v[88:91], v[210:213], v[0:15]
	v_mfma_f32_32x32x16_f16 v[0:15], v[92:95], v[214:217], v[0:15]
	s_nop 8
	v_max_i32_e32 v16, 0, v16
	v_max_i32_e32 v17, 0, v17
	v_fma_f32 v238, v16, v68, 0
	v_fma_f32 v239, v17, v69, 0
	v_max_i32_e32 v18, 0, v18
	v_max_i32_e32 v19, 0, v19
	v_fma_f32 v238, v18, v70, v238
	v_mfma_f32_32x32x16_f16 v[0:15], v[96:99], v[218:221], v[0:15]
	v_fma_f32 v239, v19, v71, v239
	v_max_i32_e32 v20, 0, v20
	v_max_i32_e32 v21, 0, v21
	v_fma_f32 v238, v20, v72, v238
	v_fma_f32 v239, v21, v73, v239
	v_max_i32_e32 v22, 0, v22
	v_max_i32_e32 v23, 0, v23
	v_mfma_f32_32x32x16_f16 v[0:15], v[100:103], v[222:225], v[0:15]
	v_fma_f32 v238, v22, v74, v238
	v_fma_f32 v239, v23, v75, v239
	v_max_i32_e32 v24, 0, v24
	v_max_i32_e32 v25, 0, v25
	v_fma_f32 v238, v24, v76, v238
	v_fma_f32 v239, v25, v77, v239
	v_mfma_f32_32x32x16_f16 v[0:15], v[104:107], v[226:229], v[0:15]
	v_max_i32_e32 v26, 0, v26
	v_max_i32_e32 v27, 0, v27
	v_fma_f32 v238, v26, v78, v238
	v_fma_f32 v239, v27, v79, v239
	v_max_i32_e32 v28, 0, v28
	v_max_i32_e32 v29, 0, v29
	v_mfma_f32_32x32x16_f16 v[0:15], v[108:111], v[230:233], v[0:15]
	v_fma_f32 v238, v28, v80, v238
	v_fma_f32 v239, v29, v81, v239
	v_max_i32_e32 v30, 0, v30
	v_max_i32_e32 v31, 0, v31
	v_fma_f32 v238, v30, v82, v238
	v_fma_f32 v239, v31, v83, v239
	v_mfma_f32_32x32x16_f16 v[0:15], v[112:115], v[234:237], v[0:15]
	s_waitcnt lgkmcnt(0)
; #define LAS __attribute__((address_space(3)))
; DI void indexer_tile(const LAS unsigned char* buf, const f16x8 (&af)[2][8], const f32x4 (&wv)[2][4], float* sc0, float* sc1, int kt, int r32, int h2) {
;     typedef float f32x2_t __attribute__((ext_vector_type(2)));
;     f16x8 bfr[2][8];
; #pragma unroll
;     for (int sub = 0; sub < 2; ++sub)
; #pragma unroll
;         for (int ks = 0; ks < 8; ++ks) bfr[sub][ks] = *(const LAS f16x8*)(buf + (32 * sub + r32) * KT_ROWB + (16 * ks + 8 * h2) * 2);
;     __builtin_amdgcn_sched_barrier(0);
; #pragma unroll
;     for (int sub = 0; sub < 2; ++sub) {
;         f32x16 c0, c1;
; #pragma unroll
;         for (int i = 0; i < 16; ++i) { c0[i] = 0.f; c1[i] = 0.f; }
; #pragma unroll
;         for (int ks = 0; ks < 8; ++ks) { c0 = __builtin_amdgcn_mfma_f32_32x32x16_f16(af[0][ks], bfr[sub][ks], c0, 0, 0, 0); c1 = __builtin_amdgcn_mfma_f32_32x32x16_f16(af[1][ks], bfr[sub][ks], c1, 0, 0, 0); }
;         f32x2_t a0 = {0.f, 0.f}, a1 = {0.f, 0.f};
; #pragma unroll
;         for (int q = 0; q < 4; ++q)
; #pragma unroll
;             for (int e = 0; e < 4; e += 2) {
;                 const f32x2_t r0 = {relu1(c0[4 * q + e]), relu1(c0[4 * q + e + 1])};
;                 const f32x2_t r1 = {relu1(c1[4 * q + e]), relu1(c1[4 * q + e + 1])};
;                 const f32x2_t w0 = {wv[0][q][e], wv[0][q][e + 1]}, w1 = {wv[1][q][e], wv[1][q][e + 1]};
;                 a0 = __builtin_elementwise_fma(r0, w0, a0); a1 = __builtin_elementwise_fma(r1, w1, a1); }
;         float s0 = a0.x + a0.y, s1 = a1.x + a1.y;
;         s0 += __shfl_xor(s0, 32); s1 += __shfl_xor(s1, 32);
;         if (h2 == 0) { sc0[kt * 64 + 32 * sub + r32] = s0; sc1[kt * 64 + 32 * sub + r32] = s1; }
; DI void indexer_phase(const unsigned short* QI, const unsigned short* KI16, const float* WI, float* SC, LAS unsigned char* lds, int tid, int bid, int G) {
;     ...
;             for (int kt = 0; kt < nt; kt += 2) {
;                 if (kt + 2 < nt) { const unsigned short* p = src + (size_t)(kt + 2) * 64 * 128; a0 = *(const u32x4*)p; a1 = *(const u32x4*)(p + 32 * 128); }
;                 indexer_tile(buf0, af, wv, sc0, sc1, kt, r32, h2);
;                 if (kt + 1 < nt) { *(LAS u32x4*)(buf1 + key0 * KT_ROWB + ch * 16) = b0; *(LAS u32x4*)(buf1 + (key0 + 32) * KT_ROWB + ch * 16) = b1; }
;                 __syncthreads();
;                 if (kt + 1 >= nt) break;
	v_mfma_f32_32x32x16_f16 v[16:31], v[36:39], v[176:179], 0
	v_mfma_f32_32x32x16_f16 v[16:31], v[40:43], v[172:175], v[16:31]
	v_mfma_f32_32x32x16_f16 v[16:31], v[44:47], v[168:171], v[16:31]
	s_nop 8
	v_max_i32_e32 v0, 0, v0
	v_max_i32_e32 v1, 0, v1
	v_fma_f32 v240, v0, v116, 0
	v_fma_f32 v241, v1, v117, 0
	v_max_i32_e32 v2, 0, v2
	v_max_i32_e32 v3, 0, v3
	v_fma_f32 v240, v2, v118, v240
	v_mfma_f32_32x32x16_f16 v[16:31], v[48:51], v[164:167], v[16:31]
	v_fma_f32 v241, v3, v119, v241
	v_max_i32_e32 v4, 0, v4
	v_max_i32_e32 v5, 0, v5
	v_fma_f32 v240, v4, v120, v240
	v_fma_f32 v241, v5, v121, v241
	v_max_i32_e32 v6, 0, v6
	v_max_i32_e32 v7, 0, v7
	v_mfma_f32_32x32x16_f16 v[16:31], v[52:55], v[160:163], v[16:31]
	v_fma_f32 v240, v6, v122, v240
	v_fma_f32 v241, v7, v123, v241
	v_max_i32_e32 v8, 0, v8
	v_max_i32_e32 v9, 0, v9
	v_fma_f32 v240, v8, v124, v240
	v_fma_f32 v241, v9, v125, v241
	v_mfma_f32_32x32x16_f16 v[16:31], v[56:59], v[156:159], v[16:31]
	v_max_i32_e32 v10, 0, v10
	v_max_i32_e32 v11, 0, v11
	v_fma_f32 v240, v10, v126, v240
	v_fma_f32 v241, v11, v127, v241
	v_max_i32_e32 v12, 0, v12
	v_max_i32_e32 v13, 0, v13
	v_mfma_f32_32x32x16_f16 v[16:31], v[60:63], v[152:155], v[16:31]
	v_fma_f32 v240, v12, v128, v240
	v_fma_f32 v241, v13, v129, v241
	v_max_i32_e32 v14, 0, v14
	v_max_i32_e32 v15, 0, v15
	v_fma_f32 v240, v14, v130, v240
	v_fma_f32 v241, v15, v131, v241
	v_mfma_f32_32x32x16_f16 v[16:31], v[64:67], v[148:151], v[16:31]
	v_add_f32_e32 v242, v238, v239
	v_add_f32_e32 v243, v240, v241
	v_lshl_add_u32 v244, v32, 2, v248
	s_nop 0
	v_permlane32_swap_b32_e32 v242, v243
	v_add_f32_e32 v242, v242, v243
	global_store_dword v244, v242, s[18:19]
	v_mfma_f32_32x32x16_f16 v[0:15], v[84:87], v[176:179], 0
	v_mfma_f32_32x32x16_f16 v[0:15], v[88:91], v[172:175], v[0:15]
	v_mfma_f32_32x32x16_f16 v[0:15], v[92:95], v[168:171], v[0:15]
	s_nop 8
	v_max_i32_e32 v16, 0, v16
	v_max_i32_e32 v17, 0, v17
	v_fma_f32 v238, v16, v68, 0
	v_fma_f32 v239, v17, v69, 0
	v_max_i32_e32 v18, 0, v18
	v_max_i32_e32 v19, 0, v19
	v_fma_f32 v238, v18, v70, v238
	v_mfma_f32_32x32x16_f16 v[0:15], v[96:99], v[164:167], v[0:15]
	v_fma_f32 v239, v19, v71, v239
	v_max_i32_e32 v20, 0, v20
	v_max_i32_e32 v21, 0, v21
	v_fma_f32 v238, v20, v72, v238
	v_fma_f32 v239, v21, v73, v239
	v_max_i32_e32 v22, 0, v22
	v_max_i32_e32 v23, 0, v23
	v_mfma_f32_32x32x16_f16 v[0:15], v[100:103], v[160:163], v[0:15]
	v_fma_f32 v238, v22, v74, v238
	v_fma_f32 v239, v23, v75, v239
	v_max_i32_e32 v24, 0, v24
	v_max_i32_e32 v25, 0, v25
	v_fma_f32 v238, v24, v76, v238
	v_fma_f32 v239, v25, v77, v239
	v_mfma_f32_32x32x16_f16 v[0:15], v[104:107], v[156:159], v[0:15]
	v_max_i32_e32 v26, 0, v26
	v_max_i32_e32 v27, 0, v27
	v_fma_f32 v238, v26, v78, v238
	v_fma_f32 v239, v27, v79, v239
	v_max_i32_e32 v28, 0, v28
	v_max_i32_e32 v29, 0, v29
	v_mfma_f32_32x32x16_f16 v[0:15], v[108:111], v[152:155], v[0:15]
	v_fma_f32 v238, v28, v80, v238
	v_fma_f32 v239, v29, v81, v239
	v_max_i32_e32 v30, 0, v30
	v_max_i32_e32 v31, 0, v31
	v_fma_f32 v238, v30, v82, v238
	v_fma_f32 v239, v31, v83, v239
	v_mfma_f32_32x32x16_f16 v[0:15], v[112:115], v[148:151], v[0:15]
	s_nop 11
	v_max_i32_e32 v0, 0, v0
	v_max_i32_e32 v1, 0, v1
	v_fma_f32 v240, v0, v116, 0
	v_fma_f32 v241, v1, v117, 0
	v_max_i32_e32 v2, 0, v2
	v_max_i32_e32 v3, 0, v3
	v_fma_f32 v240, v2, v118, v240
	v_fma_f32 v241, v3, v119, v241
	v_max_i32_e32 v4, 0, v4
	v_max_i32_e32 v5, 0, v5
	v_fma_f32 v240, v4, v120, v240
	v_fma_f32 v241, v5, v121, v241
	v_max_i32_e32 v6, 0, v6
	v_max_i32_e32 v7, 0, v7
	v_fma_f32 v240, v6, v122, v240
	v_fma_f32 v241, v7, v123, v241
	v_max_i32_e32 v8, 0, v8
	v_max_i32_e32 v9, 0, v9
	v_fma_f32 v240, v8, v124, v240
	v_fma_f32 v241, v9, v125, v241
	v_max_i32_e32 v10, 0, v10
	v_max_i32_e32 v11, 0, v11
	v_fma_f32 v240, v10, v126, v240
	v_fma_f32 v241, v11, v127, v241
	v_max_i32_e32 v12, 0, v12
	v_max_i32_e32 v13, 0, v13
	v_fma_f32 v240, v12, v128, v240
	v_fma_f32 v241, v13, v129, v241
	v_max_i32_e32 v14, 0, v14
	v_max_i32_e32 v15, 0, v15
	v_fma_f32 v240, v14, v130, v240
	v_fma_f32 v241, v15, v131, v241
	v_add_f32_e32 v242, v238, v239
	v_add_f32_e32 v243, v240, v241
	v_lshl_add_u32 v244, v32, 2, v248
	s_nop 0
	v_permlane32_swap_b32_e32 v242, v243
	v_add_f32_e32 v242, v242, v243
	global_store_dword v244, v242, s[18:19] offset:128
	s_add_i32 s27, s11, -3
	s_cmp_lt_i32 s27, s41
	s_cselect_b64 s[24:25], -1, 0
	s_cmp_ge_i32 s27, s41
	s_cbranch_scc1 .LBB0_1833
	s_waitcnt vmcnt(4)
	ds_write_b128 v209, v[140:143] offset:17408
	ds_write_b128 v209, v[144:147] offset:26112

; #define LAS __attribute__((address_space(3)))
; DI void indexer_tile(const LAS unsigned char* buf, const f16x8 (&af)[2][8], const f32x4 (&wv)[2][4], float* sc0, float* sc1, int kt, int r32, int h2) {
;     typedef float f32x2_t __attribute__((ext_vector_type(2)));
;     f16x8 bfr[2][8];
; #pragma unroll
;     for (int sub = 0; sub < 2; ++sub)
; #pragma unroll
;         for (int ks = 0; ks < 8; ++ks) bfr[sub][ks] = *(const LAS f16x8*)(buf + (32 * sub + r32) * KT_ROWB + (16 * ks + 8 * h2) * 2);
;     __builtin_amdgcn_sched_barrier(0);
; #pragma unroll
;     for (int sub = 0; sub < 2; ++sub) {
;         f32x16 c0, c1;
; #pragma unroll
;         for (int i = 0; i < 16; ++i) { c0[i] = 0.f; c1[i] = 0.f; }
; #pragma unroll
;         for (int ks = 0; ks < 8; ++ks) { c0 = __builtin_amdgcn_mfma_f32_32x32x16_f16(af[0][ks], bfr[sub][ks], c0, 0, 0, 0); c1 = __builtin_amdgcn_mfma_f32_32x32x16_f16(af[1][ks], bfr[sub][ks], c1, 0, 0, 0); }
;         f32x2_t a0 = {0.f, 0.f}, a1 = {0.f, 0.f};
; #pragma unroll
;         for (int q = 0; q < 4; ++q)
; #pragma unroll
;             for (int e = 0; e < 4; e += 2) {
;                 const f32x2_t r0 = {relu1(c0[4 * q + e]), relu1(c0[4 * q + e + 1])};
;                 const f32x2_t r1 = {relu1(c1[4 * q + e]), relu1(c1[4 * q + e + 1])};
;                 const f32x2_t w0 = {wv[0][q][e], wv[0][q][e + 1]}, w1 = {wv[1][q][e], wv[1][q][e + 1]};
;                 a0 = __builtin_elementwise_fma(r0, w0, a0); a1 = __builtin_elementwise_fma(r1, w1, a1); }
;         float s0 = a0.x + a0.y, s1 = a1.x + a1.y;
;         s0 += __shfl_xor(s0, 32); s1 += __shfl_xor(s1, 32);
;         if (h2 == 0) { sc0[kt * 64 + 32 * sub + r32] = s0; sc1[kt * 64 + 32 * sub + r32] = s1; }
.LBB0_1836:
	ds_read_b128 v[0:3], v207 offset:17408
	ds_read_b128 v[210:213], v207 offset:17440
	ds_read_b128 v[214:217], v207 offset:17472
	ds_read_b128 v[218:221], v207 offset:17504
	ds_read_b128 v[222:225], v207 offset:17536
	ds_read_b128 v[226:229], v207 offset:17568
	ds_read_b128 v[230:233], v207 offset:17600
	ds_read_b128 v[234:237], v207 offset:17632
	ds_read_b128 v[176:179], v207 offset:26112
	ds_read_b128 v[172:175], v207 offset:26144
	ds_read_b128 v[168:171], v207 offset:26176
	ds_read_b128 v[164:167], v207 offset:26208
	ds_read_b128 v[160:163], v207 offset:26240
	ds_read_b128 v[156:159], v207 offset:26272
	ds_read_b128 v[152:155], v207 offset:26304
	ds_read_b128 v[148:151], v207 offset:26336
	s_waitcnt lgkmcnt(15)
	v_mfma_f32_32x32x16_f16 v[16:31], v[36:39], v[0:3], 0
	s_waitcnt lgkmcnt(14)
	v_mfma_f32_32x32x16_f16 v[16:31], v[40:43], v[210:213], v[16:31]
	s_waitcnt lgkmcnt(13)
	v_mfma_f32_32x32x16_f16 v[16:31], v[44:47], v[214:217], v[16:31]
	s_waitcnt lgkmcnt(12)
	v_mfma_f32_32x32x16_f16 v[16:31], v[48:51], v[218:221], v[16:31]
	s_waitcnt lgkmcnt(11)
	v_mfma_f32_32x32x16_f16 v[16:31], v[52:55], v[222:225], v[16:31]
	s_waitcnt lgkmcnt(10)
	v_mfma_f32_32x32x16_f16 v[16:31], v[56:59], v[226:229], v[16:31]
	s_waitcnt lgkmcnt(9)
	v_mfma_f32_32x32x16_f16 v[16:31], v[60:63], v[230:233], v[16:31]
	s_waitcnt lgkmcnt(8)
	v_mfma_f32_32x32x16_f16 v[16:31], v[64:67], v[234:237], v[16:31]
	v_mfma_f32_32x32x16_f16 v[0:15], v[84:87], v[0:3], 0
	v_mfma_f32_32x32x16_f16 v[0:15], v[88:91], v[210:213], v[0:15]
	v_mfma_f32_32x32x16_f16 v[0:15], v[92:95], v[214:217], v[0:15]
	s_nop 8
	v_max_i32_e32 v16, 0, v16
	v_max_i32_e32 v17, 0, v17
	v_fma_f32 v238, v16, v68, 0
	v_fma_f32 v239, v17, v69, 0
	v_max_i32_e32 v18, 0, v18
	v_max_i32_e32 v19, 0, v19
	v_fma_f32 v238, v18, v70, v238
	v_mfma_f32_32x32x16_f16 v[0:15], v[96:99], v[218:221], v[0:15]
	v_fma_f32 v239, v19, v71, v239
	v_max_i32_e32 v20, 0, v20
	v_max_i32_e32 v21, 0, v21
	v_fma_f32 v238, v20, v72, v238
	v_fma_f32 v239, v21, v73, v239
	v_max_i32_e32 v22, 0, v22
	v_max_i32_e32 v23, 0, v23
	v_mfma_f32_32x32x16_f16 v[0:15], v[100:103], v[222:225], v[0:15]
	v_fma_f32 v238, v22, v74, v238
	v_fma_f32 v239, v23, v75, v239
	v_max_i32_e32 v24, 0, v24
	v_max_i32_e32 v25, 0, v25
	v_fma_f32 v238, v24, v76, v238
	v_fma_f32 v239, v25, v77, v239
	v_mfma_f32_32x32x16_f16 v[0:15], v[104:107], v[226:229], v[0:15]
	v_max_i32_e32 v26, 0, v26
	v_max_i32_e32 v27, 0, v27
	v_fma_f32 v238, v26, v78, v238
	v_fma_f32 v239, v27, v79, v239
	v_max_i32_e32 v28, 0, v28
	v_max_i32_e32 v29, 0, v29
	v_mfma_f32_32x32x16_f16 v[0:15], v[108:111], v[230:233], v[0:15]
	v_fma_f32 v238, v28, v80, v238
	v_fma_f32 v239, v29, v81, v239
	v_max_i32_e32 v30, 0, v30
	v_max_i32_e32 v31, 0, v31
	v_fma_f32 v238, v30, v82, v238
	v_fma_f32 v239, v31, v83, v239
	v_mfma_f32_32x32x16_f16 v[0:15], v[112:115], v[234:237], v[0:15]
	s_waitcnt lgkmcnt(0)
; #define LAS __attribute__((address_space(3)))
; DI void indexer_tile(const LAS unsigned char* buf, const f16x8 (&af)[2][8], const f32x4 (&wv)[2][4], float* sc0, float* sc1, int kt, int r32, int h2) {
;     typedef float f32x2_t __attribute__((ext_vector_type(2)));
;     f16x8 bfr[2][8];
; #pragma unroll
;     for (int sub = 0; sub < 2; ++sub)
; #pragma unroll
;         for (int ks = 0; ks < 8; ++ks) bfr[sub][ks] = *(const LAS f16x8*)(buf + (32 * sub + r32) * KT_ROWB + (16 * ks + 8 * h2) * 2);
;     __builtin_amdgcn_sched_barrier(0);
; #pragma unroll
;     for (int sub = 0; sub < 2; ++sub) {
;         f32x16 c0, c1;
; #pragma unroll
;         for (int i = 0; i < 16; ++i) { c0[i] = 0.f; c1[i] = 0.f; }
; #pragma unroll
;         for (int ks = 0; ks < 8; ++ks) { c0 = __builtin_amdgcn_mfma_f32_32x32x16_f16(af[0][ks], bfr[sub][ks], c0, 0, 0, 0); c1 = __builtin_amdgcn_mfma_f32_32x32x16_f16(af[1][ks], bfr[sub][ks], c1, 0, 0, 0); }
;         f32x2_t a0 = {0.f, 0.f}, a1 = {0.f, 0.f};
; #pragma unroll
;         for (int q = 0; q < 4; ++q)
; #pragma unroll
;             for (int e = 0; e < 4; e += 2) {
;                 const f32x2_t r0 = {relu1(c0[4 * q + e]), relu1(c0[4 * q + e + 1])};
;                 const f32x2_t r1 = {relu1(c1[4 * q + e]), relu1(c1[4 * q + e + 1])};
;                 const f32x2_t w0 = {wv[0][q][e], wv[0][q][e + 1]}, w1 = {wv[1][q][e], wv[1][q][e + 1]};
;                 a0 = __builtin_elementwise_fma(r0, w0, a0); a1 = __builtin_elementwise_fma(r1, w1, a1); }
;         float s0 = a0.x + a0.y, s1 = a1.x + a1.y;
;         s0 += __shfl_xor(s0, 32); s1 += __shfl_xor(s1, 32);
;         if (h2 == 0) { sc0[kt * 64 + 32 * sub + r32] = s0; sc1[kt * 64 + 32 * sub + r32] = s1; }
; DI void indexer_phase(const unsigned short* QI, const unsigned short* KI16, const float* WI, float* SC, LAS unsigned char* lds, int tid, int bid, int G) {
;     ...
;             for (int kt = 0; kt < nt; kt += 2) {
;                 if (kt + 2 < nt) { const unsigned short* p = src + (size_t)(kt + 2) * 64 * 128; a0 = *(const u32x4*)p; a1 = *(const u32x4*)(p + 32 * 128); }
;                 indexer_tile(buf0, af, wv, sc0, sc1, kt, r32, h2);
;                 if (kt + 1 < nt) { *(LAS u32x4*)(buf1 + key0 * KT_ROWB + ch * 16) = b0; *(LAS u32x4*)(buf1 + (key0 + 32) * KT_ROWB + ch * 16) = b1; }
;                 __syncthreads();
;                 if (kt + 1 >= nt) break;
	v_mfma_f32_32x32x16_f16 v[16:31], v[36:39], v[176:179], 0
	v_mfma_f32_32x32x16_f16 v[16:31], v[40:43], v[172:175], v[16:31]
	v_mfma_f32_32x32x16_f16 v[16:31], v[44:47], v[168:171], v[16:31]
	s_nop 8
	v_max_i32_e32 v0, 0, v0
	v_max_i32_e32 v1, 0, v1
	v_fma_f32 v240, v0, v116, 0
	v_fma_f32 v241, v1, v117, 0
	v_max_i32_e32 v2, 0, v2
	v_max_i32_e32 v3, 0, v3
	v_fma_f32 v240, v2, v118, v240
	v_mfma_f32_32x32x16_f16 v[16:31], v[48:51], v[164:167], v[16:31]
	v_fma_f32 v241, v3, v119, v241
	v_max_i32_e32 v4, 0, v4
	v_max_i32_e32 v5, 0, v5
	v_fma_f32 v240, v4, v120, v240
	v_fma_f32 v241, v5, v121, v241
	v_max_i32_e32 v6, 0, v6
	v_max_i32_e32 v7, 0, v7
	v_mfma_f32_32x32x16_f16 v[16:31], v[52:55], v[160:163], v[16:31]
	v_fma_f32 v240, v6, v122, v240
	v_fma_f32 v241, v7, v123, v241
	v_max_i32_e32 v8, 0, v8
	v_max_i32_e32 v9, 0, v9
	v_fma_f32 v240, v8, v124, v240
	v_fma_f32 v241, v9, v125, v241
	v_mfma_f32_32x32x16_f16 v[16:31], v[56:59], v[156:159], v[16:31]
	v_max_i32_e32 v10, 0, v10
	v_max_i32_e32 v11, 0, v11
	v_fma_f32 v240, v10, v126, v240
	v_fma_f32 v241, v11, v127, v241
	v_max_i32_e32 v12, 0, v12
	v_max_i32_e32 v13, 0, v13
	v_mfma_f32_32x32x16_f16 v[16:31], v[60:63], v[152:155], v[16:31]
	v_fma_f32 v240, v12, v128, v240
	v_fma_f32 v241, v13, v129, v241
	v_max_i32_e32 v14, 0, v14
	v_max_i32_e32 v15, 0, v15
	v_fma_f32 v240, v14, v130, v240
	v_fma_f32 v241, v15, v131, v241
	v_mfma_f32_32x32x16_f16 v[16:31], v[64:67], v[148:151], v[16:31]
	v_add_f32_e32 v242, v238, v239
	v_add_f32_e32 v243, v240, v241
	v_lshl_add_u32 v244, v32, 2, v248
	s_nop 0
	v_permlane32_swap_b32_e32 v242, v243
	v_add_f32_e32 v242, v242, v243
	global_store_dword v244, v242, s[18:19] offset:256
	v_mfma_f32_32x32x16_f16 v[0:15], v[84:87], v[176:179], 0
	v_mfma_f32_32x32x16_f16 v[0:15], v[88:91], v[172:175], v[0:15]
	v_mfma_f32_32x32x16_f16 v[0:15], v[92:95], v[168:171], v[0:15]
	s_nop 8
	v_max_i32_e32 v16, 0, v16
	v_max_i32_e32 v17, 0, v17
	v_fma_f32 v238, v16, v68, 0
	v_fma_f32 v239, v17, v69, 0
	v_max_i32_e32 v18, 0, v18
	v_max_i32_e32 v19, 0, v19
	v_fma_f32 v238, v18, v70, v238
	v_mfma_f32_32x32x16_f16 v[0:15], v[96:99], v[164:167], v[0:15]
	v_fma_f32 v239, v19, v71, v239
	v_max_i32_e32 v20, 0, v20
	v_max_i32_e32 v21, 0, v21
	v_fma_f32 v238, v20, v72, v238
	v_fma_f32 v239, v21, v73, v239
	v_max_i32_e32 v22, 0, v22
	v_max_i32_e32 v23, 0, v23
	v_mfma_f32_32x32x16_f16 v[0:15], v[100:103], v[160:163], v[0:15]
	v_fma_f32 v238, v22, v74, v238
	v_fma_f32 v239, v23, v75, v239
	v_max_i32_e32 v24, 0, v24
	v_max_i32_e32 v25, 0, v25
	v_fma_f32 v238, v24, v76, v238
	v_fma_f32 v239, v25, v77, v239
	v_mfma_f32_32x32x16_f16 v[0:15], v[104:107], v[156:159], v[0:15]
	v_max_i32_e32 v26, 0, v26
	v_max_i32_e32 v27, 0, v27
	v_fma_f32 v238, v26, v78, v238
	v_fma_f32 v239, v27, v79, v239
	v_max_i32_e32 v28, 0, v28
	v_max_i32_e32 v29, 0, v29
	v_mfma_f32_32x32x16_f16 v[0:15], v[108:111], v[152:155], v[0:15]
	v_fma_f32 v238, v28, v80, v238
	v_fma_f32 v239, v29, v81, v239
	v_max_i32_e32 v30, 0, v30
	v_max_i32_e32 v31, 0, v31
	v_fma_f32 v238, v30, v82, v238
	v_fma_f32 v239, v31, v83, v239
	v_mfma_f32_32x32x16_f16 v[0:15], v[112:115], v[148:151], v[0:15]
	s_nop 11
	v_max_i32_e32 v0, 0, v0
	v_max_i32_e32 v1, 0, v1
	v_fma_f32 v240, v0, v116, 0
	v_fma_f32 v241, v1, v117, 0
	v_max_i32_e32 v2, 0, v2
	v_max_i32_e32 v3, 0, v3
	v_fma_f32 v240, v2, v118, v240
	v_fma_f32 v241, v3, v119, v241
	v_max_i32_e32 v4, 0, v4
	v_max_i32_e32 v5, 0, v5
	v_fma_f32 v240, v4, v120, v240
	v_fma_f32 v241, v5, v121, v241
	v_max_i32_e32 v6, 0, v6
	v_max_i32_e32 v7, 0, v7
	v_fma_f32 v240, v6, v122, v240
	v_fma_f32 v241, v7, v123, v241
	v_max_i32_e32 v8, 0, v8
	v_max_i32_e32 v9, 0, v9
	v_fma_f32 v240, v8, v124, v240
	v_fma_f32 v241, v9, v125, v241
	v_max_i32_e32 v10, 0, v10
	v_max_i32_e32 v11, 0, v11
	v_fma_f32 v240, v10, v126, v240
	v_fma_f32 v241, v11, v127, v241
	v_max_i32_e32 v12, 0, v12
	v_max_i32_e32 v13, 0, v13
	v_fma_f32 v240, v12, v128, v240
	v_fma_f32 v241, v13, v129, v241
	v_max_i32_e32 v14, 0, v14
	v_max_i32_e32 v15, 0, v15
	v_fma_f32 v240, v14, v130, v240
	v_fma_f32 v241, v15, v131, v241
	v_add_f32_e32 v242, v238, v239
	v_add_f32_e32 v243, v240, v241
	v_lshl_add_u32 v244, v32, 2, v248
	s_nop 0
	v_permlane32_swap_b32_e32 v242, v243
	v_add_f32_e32 v242, v242, v243
	global_store_dword v244, v242, s[18:19] offset:384
	s_andn2_b64 vcc, exec, s[22:23]
	s_cbranch_vccnz .LBB0_1824
	s_waitcnt vmcnt(4)
	ds_write_b128 v209, v[132:135]
	ds_write_b128 v209, v[136:139] offset:8704
	s_branch .LBB0_1824

; #define LAS __attribute__((address_space(3)))
; DI size_t sc_row_off(int b, int s) { const int qb = s >> 7; return ((size_t)(b * 2080 + ((qb * (qb + 1)) >> 1))) * 16384 + (size_t)(s & 127) * ((qb + 1) * 128); }
; DI void indexer_phase(const unsigned short* QI, const unsigned short* KI16, const float* WI, float* SC, LAS unsigned char* lds, int tid, int bid, int G) {
;     ...
;             const int b = it >> 1, gi = (it & 1) ? (511 - v) : v; const int tb = 16 * gi;
;             const int nt = ((tb + 15) >> 6) + 1;
;             f16x8 af[2][8]; f32x4 wv[2][4];
; #pragma unroll
;             for (int tq = 0; tq < 2; ++tq) { const size_t tg = (size_t)b * SEQ + tb + 2 * w + tq;
; #pragma unroll
;                 for (int ks = 0; ks < 8; ++ks) af[tq][ks] = *(const f16x8*)(QI + tg * 4096 + r32 * 128 + 16 * ks + 8 * h2);
; #pragma unroll
;                 for (int q = 0; q < 4; ++q) wv[tq][q] = *(const f32x4*)(WI + tg * 32 + 8 * q + 4 * h2); }
;             float* sc0 = SC + sc_row_off(b, tb + 2 * w); float* sc1 = SC + sc_row_off(b, tb + 2 * w + 1);
;             const unsigned short* src = KI16 + (size_t)b * SEQ * 128 + (size_t)key0 * 128 + ch * 8;
;             u32x4 a0, a1, b0 = {0u, 0u, 0u, 0u}, b1 = {0u, 0u, 0u, 0u};
;             a0 = *(const u32x4*)src; a1 = *(const u32x4*)(src + 32 * 128);
;             if (nt > 1) { b0 = *(const u32x4*)(src + 64 * 128); b1 = *(const u32x4*)(src + 96 * 128); }
;             __syncthreads();
;             *(LAS u32x4*)(buf0 + key0 * KT_ROWB + ch * 16) = a0; *(LAS u32x4*)(buf0 + (key0 + 32) * KT_ROWB + ch * 16) = a1;
;             __syncthreads();
.LBB0_1843:
	s_sub_i32 s11, 0x1ff, s40
	s_lshl_b32 s45, s11, 4
	s_add_u32 s18, s45, s36
	s_addc_u32 s19, 0, s37
	s_lshl_b64 s[20:21], s[18:19], 13
	v_lshl_add_u64 v[0:1], v[180:181], 0, s[20:21]
	s_lshl_b64 s[20:21], s[18:19], 7
	s_or_b32 s18, s18, 1
	global_load_dwordx4 v[34:37], v[0:1], off
	global_load_dwordx4 v[38:41], v[0:1], off offset:32
	global_load_dwordx4 v[42:45], v[0:1], off offset:64
	global_load_dwordx4 v[46:49], v[0:1], off offset:96
	global_load_dwordx4 v[50:53], v[0:1], off offset:128
	global_load_dwordx4 v[54:57], v[0:1], off offset:160
	global_load_dwordx4 v[58:61], v[0:1], off offset:192
	global_load_dwordx4 v[62:65], v[0:1], off offset:224
	v_lshl_add_u64 v[0:1], v[182:183], 0, s[20:21]
	s_lshl_b64 s[20:21], s[18:19], 13
	global_load_dwordx4 v[66:69], v[0:1], off
	global_load_dwordx4 v[70:73], v[0:1], off offset:32
	global_load_dwordx4 v[74:77], v[0:1], off offset:64
	global_load_dwordx4 v[78:81], v[0:1], off offset:96
	v_lshl_add_u64 v[0:1], v[180:181], 0, s[20:21]
	global_load_dwordx4 v[82:85], v[0:1], off
	global_load_dwordx4 v[86:89], v[0:1], off offset:32
	global_load_dwordx4 v[90:93], v[0:1], off offset:64
	global_load_dwordx4 v[94:97], v[0:1], off offset:96
	global_load_dwordx4 v[98:101], v[0:1], off offset:128
	global_load_dwordx4 v[102:105], v[0:1], off offset:160
	global_load_dwordx4 v[106:109], v[0:1], off offset:192
	global_load_dwordx4 v[110:113], v[0:1], off offset:224
	s_lshl_b64 s[18:19], s[18:19], 7
	v_lshl_add_u64 v[0:1], v[182:183], 0, s[18:19]
	global_load_dwordx4 v[130:133], v[184:185], off
	global_load_dwordx4 v[138:141], v[186:187], off
	global_load_dwordx4 v[114:117], v[0:1], off
	global_load_dwordx4 v[118:121], v[0:1], off offset:32
	global_load_dwordx4 v[134:137], v[190:191], off
	global_load_dwordx4 v[142:145], v[188:189], off
	global_load_dwordx4 v[122:125], v[0:1], off offset:64
	global_load_dwordx4 v[126:129], v[0:1], off offset:96
	s_lshr_b32 s42, s11, 2
	s_add_i32 s11, s45, s36
	s_ashr_i32 s18, s11, 7
	s_add_i32 s19, s18, 1
	s_mul_i32 s18, s19, s18
	s_ashr_i32 s18, s18, 1
	s_lshl_b32 s26, s19, 7
	s_ashr_i32 s19, s18, 31
	s_and_b32 s11, s11, 0x7e
	s_lshl_b64 s[22:23], s[18:19], 16
	s_mul_hi_i32 s21, s26, s11
	s_mul_i32 s20, s26, s11
	s_add_u32 s27, s17, s22
	s_addc_u32 s28, s33, s23
	s_lshl_b64 s[20:21], s[20:21], 2
	s_add_u32 s24, s27, s20
	s_addc_u32 s25, s28, s21
	s_or_b32 s11, s11, 1
	s_mul_hi_i32 s23, s26, s11
	s_mul_i32 s22, s26, s11
	s_lshl_b64 s[22:23], s[22:23], 2
	s_add_u32 s26, s27, s22
	s_addc_u32 s27, s28, s23
	s_mov_b32 s11, 3
	v_mov_b32_e32 v32, v206
	v_mov_b64_e32 v[178:179], v[200:201]
	s_barrier
	s_waitcnt vmcnt(7)
	ds_write_b128 v209, v[130:133]
	s_waitcnt vmcnt(0)
	ds_write_b128 v209, v[138:141] offset:8704
	s_waitcnt lgkmcnt(0)
	s_barrier
	s_sub_u32 s98, s26, s24
	v_mov_b32_e32 v248, s98
	s_nop 0
	v_cndmask_b32_e64 v248, v248, 0, s[4:5]
	s_branch .LBB0_1845

; #define LAS __attribute__((address_space(3)))
; DI void indexer_tile(const LAS unsigned char* buf, const f16x8 (&af)[2][8], const f32x4 (&wv)[2][4], float* sc0, float* sc1, int kt, int r32, int h2) {
;     typedef float f32x2_t __attribute__((ext_vector_type(2)));
;     f16x8 bfr[2][8];
; #pragma unroll
;     for (int sub = 0; sub < 2; ++sub)
; #pragma unroll
;         for (int ks = 0; ks < 8; ++ks) bfr[sub][ks] = *(const LAS f16x8*)(buf + (32 * sub + r32) * KT_ROWB + (16 * ks + 8 * h2) * 2);
;     __builtin_amdgcn_sched_barrier(0);
; #pragma unroll
;     for (int sub = 0; sub < 2; ++sub) {
;         f32x16 c0, c1;
; #pragma unroll
;         for (int i = 0; i < 16; ++i) { c0[i] = 0.f; c1[i] = 0.f; }
; #pragma unroll
;         for (int ks = 0; ks < 8; ++ks) { c0 = __builtin_amdgcn_mfma_f32_32x32x16_f16(af[0][ks], bfr[sub][ks], c0, 0, 0, 0); c1 = __builtin_amdgcn_mfma_f32_32x32x16_f16(af[1][ks], bfr[sub][ks], c1, 0, 0, 0); }
;         f32x2_t a0 = {0.f, 0.f}, a1 = {0.f, 0.f};
; #pragma unroll
;         for (int q = 0; q < 4; ++q)
; #pragma unroll
;             for (int e = 0; e < 4; e += 2) {
;                 const f32x2_t r0 = {relu1(c0[4 * q + e]), relu1(c0[4 * q + e + 1])};
;                 const f32x2_t r1 = {relu1(c1[4 * q + e]), relu1(c1[4 * q + e + 1])};
;                 const f32x2_t w0 = {wv[0][q][e], wv[0][q][e + 1]}, w1 = {wv[1][q][e], wv[1][q][e + 1]};
;                 a0 = __builtin_elementwise_fma(r0, w0, a0); a1 = __builtin_elementwise_fma(r1, w1, a1); }
;         float s0 = a0.x + a0.y, s1 = a1.x + a1.y;
;         s0 += __shfl_xor(s0, 32); s1 += __shfl_xor(s1, 32);
;         if (h2 == 0) { sc0[kt * 64 + 32 * sub + r32] = s0; sc1[kt * 64 + 32 * sub + r32] = s1; }
.LBB0_1847:
	ds_read_b128 v[0:3], v207
	ds_read_b128 v[210:213], v207 offset:32
	ds_read_b128 v[214:217], v207 offset:64
	ds_read_b128 v[218:221], v207 offset:96
	ds_read_b128 v[222:225], v207 offset:128
	ds_read_b128 v[226:229], v207 offset:160
	ds_read_b128 v[230:233], v207 offset:192
	ds_read_b128 v[234:237], v207 offset:224
	ds_read_b128 v[174:177], v207 offset:8704
	ds_read_b128 v[170:173], v207 offset:8736
	ds_read_b128 v[166:169], v207 offset:8768
	ds_read_b128 v[162:165], v207 offset:8800
	ds_read_b128 v[158:161], v207 offset:8832
	ds_read_b128 v[154:157], v207 offset:8864
	ds_read_b128 v[150:153], v207 offset:8896
	ds_read_b128 v[146:149], v207 offset:8928
	s_waitcnt lgkmcnt(15)
	v_mfma_f32_32x32x16_f16 v[16:31], v[34:37], v[0:3], 0
	s_waitcnt lgkmcnt(14)
	v_mfma_f32_32x32x16_f16 v[16:31], v[38:41], v[210:213], v[16:31]
	s_waitcnt lgkmcnt(13)
	v_mfma_f32_32x32x16_f16 v[16:31], v[42:45], v[214:217], v[16:31]
	s_waitcnt lgkmcnt(12)
	v_mfma_f32_32x32x16_f16 v[16:31], v[46:49], v[218:221], v[16:31]
	s_waitcnt lgkmcnt(11)
	v_mfma_f32_32x32x16_f16 v[16:31], v[50:53], v[222:225], v[16:31]
	s_waitcnt lgkmcnt(10)
	v_mfma_f32_32x32x16_f16 v[16:31], v[54:57], v[226:229], v[16:31]
	s_waitcnt lgkmcnt(9)
	v_mfma_f32_32x32x16_f16 v[16:31], v[58:61], v[230:233], v[16:31]
	s_waitcnt lgkmcnt(8)
	v_mfma_f32_32x32x16_f16 v[16:31], v[62:65], v[234:237], v[16:31]
	v_mfma_f32_32x32x16_f16 v[0:15], v[82:85], v[0:3], 0
	v_mfma_f32_32x32x16_f16 v[0:15], v[86:89], v[210:213], v[0:15]
	v_mfma_f32_32x32x16_f16 v[0:15], v[90:93], v[214:217], v[0:15]
	s_nop 8
	v_max_i32_e32 v16, 0, v16
	v_max_i32_e32 v17, 0, v17
	v_fma_f32 v238, v16, v66, 0
	v_fma_f32 v239, v17, v67, 0
	v_max_i32_e32 v18, 0, v18
	v_max_i32_e32 v19, 0, v19
	v_fma_f32 v238, v18, v68, v238
	v_mfma_f32_32x32x16_f16 v[0:15], v[94:97], v[218:221], v[0:15]
	v_fma_f32 v239, v19, v69, v239
	v_max_i32_e32 v20, 0, v20
	v_max_i32_e32 v21, 0, v21
	v_fma_f32 v238, v20, v70, v238
	v_fma_f32 v239, v21, v71, v239
	v_max_i32_e32 v22, 0, v22
	v_max_i32_e32 v23, 0, v23
	v_mfma_f32_32x32x16_f16 v[0:15], v[98:101], v[222:225], v[0:15]
	v_fma_f32 v238, v22, v72, v238
	v_fma_f32 v239, v23, v73, v239
	v_max_i32_e32 v24, 0, v24
	v_max_i32_e32 v25, 0, v25
	v_fma_f32 v238, v24, v74, v238
	v_fma_f32 v239, v25, v75, v239
	v_mfma_f32_32x32x16_f16 v[0:15], v[102:105], v[226:229], v[0:15]
	v_max_i32_e32 v26, 0, v26
	v_max_i32_e32 v27, 0, v27
	v_fma_f32 v238, v26, v76, v238
	v_fma_f32 v239, v27, v77, v239
	v_max_i32_e32 v28, 0, v28
	v_max_i32_e32 v29, 0, v29
	v_mfma_f32_32x32x16_f16 v[0:15], v[106:109], v[230:233], v[0:15]
	v_fma_f32 v238, v28, v78, v238
	v_fma_f32 v239, v29, v79, v239
	v_max_i32_e32 v30, 0, v30
	v_max_i32_e32 v31, 0, v31
	v_fma_f32 v238, v30, v80, v238
	v_fma_f32 v239, v31, v81, v239
	v_mfma_f32_32x32x16_f16 v[0:15], v[110:113], v[234:237], v[0:15]
	s_waitcnt lgkmcnt(0)
; #define LAS __attribute__((address_space(3)))
; DI void indexer_tile(const LAS unsigned char* buf, const f16x8 (&af)[2][8], const f32x4 (&wv)[2][4], float* sc0, float* sc1, int kt, int r32, int h2) {
;     typedef float f32x2_t __attribute__((ext_vector_type(2)));
;     f16x8 bfr[2][8];
; #pragma unroll
;     for (int sub = 0; sub < 2; ++sub)
; #pragma unroll
;         for (int ks = 0; ks < 8; ++ks) bfr[sub][ks] = *(const LAS f16x8*)(buf + (32 * sub + r32) * KT_ROWB + (16 * ks + 8 * h2) * 2);
;     __builtin_amdgcn_sched_barrier(0);
; #pragma unroll
;     for (int sub = 0; sub < 2; ++sub) {
;         f32x16 c0, c1;
; #pragma unroll
;         for (int i = 0; i < 16; ++i) { c0[i] = 0.f; c1[i] = 0.f; }
; #pragma unroll
;         for (int ks = 0; ks < 8; ++ks) { c0 = __builtin_amdgcn_mfma_f32_32x32x16_f16(af[0][ks], bfr[sub][ks], c0, 0, 0, 0); c1 = __builtin_amdgcn_mfma_f32_32x32x16_f16(af[1][ks], bfr[sub][ks], c1, 0, 0, 0); }
;         f32x2_t a0 = {0.f, 0.f}, a1 = {0.f, 0.f};
; #pragma unroll
;         for (int q = 0; q < 4; ++q)
; #pragma unroll
;             for (int e = 0; e < 4; e += 2) {
;                 const f32x2_t r0 = {relu1(c0[4 * q + e]), relu1(c0[4 * q + e + 1])};
;                 const f32x2_t r1 = {relu1(c1[4 * q + e]), relu1(c1[4 * q + e + 1])};
;                 const f32x2_t w0 = {wv[0][q][e], wv[0][q][e + 1]}, w1 = {wv[1][q][e], wv[1][q][e + 1]};
;                 a0 = __builtin_elementwise_fma(r0, w0, a0); a1 = __builtin_elementwise_fma(r1, w1, a1); }
;         float s0 = a0.x + a0.y, s1 = a1.x + a1.y;
;         s0 += __shfl_xor(s0, 32); s1 += __shfl_xor(s1, 32);
;         if (h2 == 0) { sc0[kt * 64 + 32 * sub + r32] = s0; sc1[kt * 64 + 32 * sub + r32] = s1; }
; DI void indexer_phase(const unsigned short* QI, const unsigned short* KI16, const float* WI, float* SC, LAS unsigned char* lds, int tid, int bid, int G) {
;     ...
;             for (int kt = 0; kt < nt; kt += 2) {
;                 if (kt + 2 < nt) { const unsigned short* p = src + (size_t)(kt + 2) * 64 * 128; a0 = *(const u32x4*)p; a1 = *(const u32x4*)(p + 32 * 128); }
;                 indexer_tile(buf0, af, wv, sc0, sc1, kt, r32, h2);
;                 if (kt + 1 < nt) { *(LAS u32x4*)(buf1 + key0 * KT_ROWB + ch * 16) = b0; *(LAS u32x4*)(buf1 + (key0 + 32) * KT_ROWB + ch * 16) = b1; }
;                 __syncthreads();
;                 if (kt + 1 >= nt) break;
	v_mfma_f32_32x32x16_f16 v[16:31], v[34:37], v[174:177], 0
	v_mfma_f32_32x32x16_f16 v[16:31], v[38:41], v[170:173], v[16:31]
	v_mfma_f32_32x32x16_f16 v[16:31], v[42:45], v[166:169], v[16:31]
	s_nop 8
	v_max_i32_e32 v0, 0, v0
	v_max_i32_e32 v1, 0, v1
	v_fma_f32 v240, v0, v114, 0
	v_fma_f32 v241, v1, v115, 0
	v_max_i32_e32 v2, 0, v2
	v_max_i32_e32 v3, 0, v3
	v_fma_f32 v240, v2, v116, v240
	v_mfma_f32_32x32x16_f16 v[16:31], v[46:49], v[162:165], v[16:31]
	v_fma_f32 v241, v3, v117, v241
	v_max_i32_e32 v4, 0, v4
	v_max_i32_e32 v5, 0, v5
	v_fma_f32 v240, v4, v118, v240
	v_fma_f32 v241, v5, v119, v241
	v_max_i32_e32 v6, 0, v6
	v_max_i32_e32 v7, 0, v7
	v_mfma_f32_32x32x16_f16 v[16:31], v[50:53], v[158:161], v[16:31]
	v_fma_f32 v240, v6, v120, v240
	v_fma_f32 v241, v7, v121, v241
	v_max_i32_e32 v8, 0, v8
	v_max_i32_e32 v9, 0, v9
	v_fma_f32 v240, v8, v122, v240
	v_fma_f32 v241, v9, v123, v241
	v_mfma_f32_32x32x16_f16 v[16:31], v[54:57], v[154:157], v[16:31]
	v_max_i32_e32 v10, 0, v10
	v_max_i32_e32 v11, 0, v11
	v_fma_f32 v240, v10, v124, v240
	v_fma_f32 v241, v11, v125, v241
	v_max_i32_e32 v12, 0, v12
	v_max_i32_e32 v13, 0, v13
	v_mfma_f32_32x32x16_f16 v[16:31], v[58:61], v[150:153], v[16:31]
	v_fma_f32 v240, v12, v126, v240
	v_fma_f32 v241, v13, v127, v241
	v_max_i32_e32 v14, 0, v14
	v_max_i32_e32 v15, 0, v15
	v_fma_f32 v240, v14, v128, v240
	v_fma_f32 v241, v15, v129, v241
	v_mfma_f32_32x32x16_f16 v[16:31], v[62:65], v[146:149], v[16:31]
	v_add_f32_e32 v242, v238, v239
	v_add_f32_e32 v243, v240, v241
	v_lshl_add_u32 v244, v32, 2, v248
	s_nop 0
	v_permlane32_swap_b32_e32 v242, v243
	v_add_f32_e32 v242, v242, v243
	global_store_dword v244, v242, s[24:25]
	v_mfma_f32_32x32x16_f16 v[0:15], v[82:85], v[174:177], 0
	v_mfma_f32_32x32x16_f16 v[0:15], v[86:89], v[170:173], v[0:15]
	v_mfma_f32_32x32x16_f16 v[0:15], v[90:93], v[166:169], v[0:15]
	s_nop 8
	v_max_i32_e32 v16, 0, v16
	v_max_i32_e32 v17, 0, v17
	v_fma_f32 v238, v16, v66, 0
	v_fma_f32 v239, v17, v67, 0
	v_max_i32_e32 v18, 0, v18
	v_max_i32_e32 v19, 0, v19
	v_fma_f32 v238, v18, v68, v238
	v_mfma_f32_32x32x16_f16 v[0:15], v[94:97], v[162:165], v[0:15]
	v_fma_f32 v239, v19, v69, v239
	v_max_i32_e32 v20, 0, v20
	v_max_i32_e32 v21, 0, v21
	v_fma_f32 v238, v20, v70, v238
	v_fma_f32 v239, v21, v71, v239
	v_max_i32_e32 v22, 0, v22
	v_max_i32_e32 v23, 0, v23
	v_mfma_f32_32x32x16_f16 v[0:15], v[98:101], v[158:161], v[0:15]
	v_fma_f32 v238, v22, v72, v238
	v_fma_f32 v239, v23, v73, v239
	v_max_i32_e32 v24, 0, v24
	v_max_i32_e32 v25, 0, v25
	v_fma_f32 v238, v24, v74, v238
	v_fma_f32 v239, v25, v75, v239
	v_mfma_f32_32x32x16_f16 v[0:15], v[102:105], v[154:157], v[0:15]
	v_max_i32_e32 v26, 0, v26
	v_max_i32_e32 v27, 0, v27
	v_fma_f32 v238, v26, v76, v238
	v_fma_f32 v239, v27, v77, v239
	v_max_i32_e32 v28, 0, v28
	v_max_i32_e32 v29, 0, v29
	v_mfma_f32_32x32x16_f16 v[0:15], v[106:109], v[150:153], v[0:15]
	v_fma_f32 v238, v28, v78, v238
	v_fma_f32 v239, v29, v79, v239
	v_max_i32_e32 v30, 0, v30
	v_max_i32_e32 v31, 0, v31
	v_fma_f32 v238, v30, v80, v238
	v_fma_f32 v239, v31, v81, v239
	v_mfma_f32_32x32x16_f16 v[0:15], v[110:113], v[146:149], v[0:15]
	s_nop 11
	v_max_i32_e32 v0, 0, v0
	v_max_i32_e32 v1, 0, v1
	v_fma_f32 v240, v0, v114, 0
	v_fma_f32 v241, v1, v115, 0
	v_max_i32_e32 v2, 0, v2
	v_max_i32_e32 v3, 0, v3
	v_fma_f32 v240, v2, v116, v240
	v_fma_f32 v241, v3, v117, v241
	v_max_i32_e32 v4, 0, v4
	v_max_i32_e32 v5, 0, v5
	v_fma_f32 v240, v4, v118, v240
	v_fma_f32 v241, v5, v119, v241
	v_max_i32_e32 v6, 0, v6
	v_max_i32_e32 v7, 0, v7
	v_fma_f32 v240, v6, v120, v240
	v_fma_f32 v241, v7, v121, v241
	v_max_i32_e32 v8, 0, v8
	v_max_i32_e32 v9, 0, v9
	v_fma_f32 v240, v8, v122, v240
	v_fma_f32 v241, v9, v123, v241
	v_max_i32_e32 v10, 0, v10
	v_max_i32_e32 v11, 0, v11
	v_fma_f32 v240, v10, v124, v240
	v_fma_f32 v241, v11, v125, v241
	v_max_i32_e32 v12, 0, v12
	v_max_i32_e32 v13, 0, v13
	v_fma_f32 v240, v12, v126, v240
	v_fma_f32 v241, v13, v127, v241
	v_max_i32_e32 v14, 0, v14
	v_max_i32_e32 v15, 0, v15
	v_fma_f32 v240, v14, v128, v240
	v_fma_f32 v241, v15, v129, v241
	v_add_f32_e32 v242, v238, v239
	v_add_f32_e32 v243, v240, v241
	v_lshl_add_u32 v244, v32, 2, v248
	s_nop 0
	v_permlane32_swap_b32_e32 v242, v243
	v_add_f32_e32 v242, v242, v243
	global_store_dword v244, v242, s[24:25] offset:128
	s_add_i32 s47, s11, -3
	s_cmp_lt_u32 s47, s42
	s_cselect_b64 s[30:31], -1, 0
	s_cmp_ge_u32 s47, s42
	s_cbranch_scc1 .LBB0_1853
	s_waitcnt vmcnt(4)
	ds_write_b128 v209, v[134:137] offset:17408
	ds_write_b128 v209, v[142:145] offset:26112

; #define LAS __attribute__((address_space(3)))
; DI void indexer_tile(const LAS unsigned char* buf, const f16x8 (&af)[2][8], const f32x4 (&wv)[2][4], float* sc0, float* sc1, int kt, int r32, int h2) {
;     typedef float f32x2_t __attribute__((ext_vector_type(2)));
;     f16x8 bfr[2][8];
; #pragma unroll
;     for (int sub = 0; sub < 2; ++sub)
; #pragma unroll
;         for (int ks = 0; ks < 8; ++ks) bfr[sub][ks] = *(const LAS f16x8*)(buf + (32 * sub + r32) * KT_ROWB + (16 * ks + 8 * h2) * 2);
;     __builtin_amdgcn_sched_barrier(0);
; #pragma unroll
;     for (int sub = 0; sub < 2; ++sub) {
;         f32x16 c0, c1;
; #pragma unroll
;         for (int i = 0; i < 16; ++i) { c0[i] = 0.f; c1[i] = 0.f; }
; #pragma unroll
;         for (int ks = 0; ks < 8; ++ks) { c0 = __builtin_amdgcn_mfma_f32_32x32x16_f16(af[0][ks], bfr[sub][ks], c0, 0, 0, 0); c1 = __builtin_amdgcn_mfma_f32_32x32x16_f16(af[1][ks], bfr[sub][ks], c1, 0, 0, 0); }
;         f32x2_t a0 = {0.f, 0.f}, a1 = {0.f, 0.f};
; #pragma unroll
;         for (int q = 0; q < 4; ++q)
; #pragma unroll
;             for (int e = 0; e < 4; e += 2) {
;                 const f32x2_t r0 = {relu1(c0[4 * q + e]), relu1(c0[4 * q + e + 1])};
;                 const f32x2_t r1 = {relu1(c1[4 * q + e]), relu1(c1[4 * q + e + 1])};
;                 const f32x2_t w0 = {wv[0][q][e], wv[0][q][e + 1]}, w1 = {wv[1][q][e], wv[1][q][e + 1]};
;                 a0 = __builtin_elementwise_fma(r0, w0, a0); a1 = __builtin_elementwise_fma(r1, w1, a1); }
;         float s0 = a0.x + a0.y, s1 = a1.x + a1.y;
;         s0 += __shfl_xor(s0, 32); s1 += __shfl_xor(s1, 32);
;         if (h2 == 0) { sc0[kt * 64 + 32 * sub + r32] = s0; sc1[kt * 64 + 32 * sub + r32] = s1; }
.LBB0_1856:
	ds_read_b128 v[0:3], v207 offset:17408
	ds_read_b128 v[210:213], v207 offset:17440
	ds_read_b128 v[214:217], v207 offset:17472
	ds_read_b128 v[218:221], v207 offset:17504
	ds_read_b128 v[222:225], v207 offset:17536
	ds_read_b128 v[226:229], v207 offset:17568
	ds_read_b128 v[230:233], v207 offset:17600
	ds_read_b128 v[234:237], v207 offset:17632
	ds_read_b128 v[174:177], v207 offset:26112
	ds_read_b128 v[170:173], v207 offset:26144
	ds_read_b128 v[166:169], v207 offset:26176
	ds_read_b128 v[162:165], v207 offset:26208
	ds_read_b128 v[158:161], v207 offset:26240
	ds_read_b128 v[154:157], v207 offset:26272
	ds_read_b128 v[150:153], v207 offset:26304
	ds_read_b128 v[146:149], v207 offset:26336
	s_waitcnt lgkmcnt(15)
	v_mfma_f32_32x32x16_f16 v[16:31], v[34:37], v[0:3], 0
	s_waitcnt lgkmcnt(14)
	v_mfma_f32_32x32x16_f16 v[16:31], v[38:41], v[210:213], v[16:31]
	s_waitcnt lgkmcnt(13)
	v_mfma_f32_32x32x16_f16 v[16:31], v[42:45], v[214:217], v[16:31]
	s_waitcnt lgkmcnt(12)
	v_mfma_f32_32x32x16_f16 v[16:31], v[46:49], v[218:221], v[16:31]
	s_waitcnt lgkmcnt(11)
	v_mfma_f32_32x32x16_f16 v[16:31], v[50:53], v[222:225], v[16:31]
	s_waitcnt lgkmcnt(10)
	v_mfma_f32_32x32x16_f16 v[16:31], v[54:57], v[226:229], v[16:31]
	s_waitcnt lgkmcnt(9)
	v_mfma_f32_32x32x16_f16 v[16:31], v[58:61], v[230:233], v[16:31]
	s_waitcnt lgkmcnt(8)
	v_mfma_f32_32x32x16_f16 v[16:31], v[62:65], v[234:237], v[16:31]
	v_mfma_f32_32x32x16_f16 v[0:15], v[82:85], v[0:3], 0
	v_mfma_f32_32x32x16_f16 v[0:15], v[86:89], v[210:213], v[0:15]
	v_mfma_f32_32x32x16_f16 v[0:15], v[90:93], v[214:217], v[0:15]
	s_nop 8
	v_max_i32_e32 v16, 0, v16
	v_max_i32_e32 v17, 0, v17
	v_fma_f32 v238, v16, v66, 0
	v_fma_f32 v239, v17, v67, 0
	v_max_i32_e32 v18, 0, v18
	v_max_i32_e32 v19, 0, v19
	v_fma_f32 v238, v18, v68, v238
	v_mfma_f32_32x32x16_f16 v[0:15], v[94:97], v[218:221], v[0:15]
	v_fma_f32 v239, v19, v69, v239
	v_max_i32_e32 v20, 0, v20
	v_max_i32_e32 v21, 0, v21
	v_fma_f32 v238, v20, v70, v238
	v_fma_f32 v239, v21, v71, v239
	v_max_i32_e32 v22, 0, v22
	v_max_i32_e32 v23, 0, v23
	v_mfma_f32_32x32x16_f16 v[0:15], v[98:101], v[222:225], v[0:15]
	v_fma_f32 v238, v22, v72, v238
	v_fma_f32 v239, v23, v73, v239
	v_max_i32_e32 v24, 0, v24
	v_max_i32_e32 v25, 0, v25
	v_fma_f32 v238, v24, v74, v238
	v_fma_f32 v239, v25, v75, v239
	v_mfma_f32_32x32x16_f16 v[0:15], v[102:105], v[226:229], v[0:15]
	v_max_i32_e32 v26, 0, v26
	v_max_i32_e32 v27, 0, v27
	v_fma_f32 v238, v26, v76, v238
	v_fma_f32 v239, v27, v77, v239
	v_max_i32_e32 v28, 0, v28
	v_max_i32_e32 v29, 0, v29
	v_mfma_f32_32x32x16_f16 v[0:15], v[106:109], v[230:233], v[0:15]
	v_fma_f32 v238, v28, v78, v238
	v_fma_f32 v239, v29, v79, v239
	v_max_i32_e32 v30, 0, v30
	v_max_i32_e32 v31, 0, v31
	v_fma_f32 v238, v30, v80, v238
	v_fma_f32 v239, v31, v81, v239
	v_mfma_f32_32x32x16_f16 v[0:15], v[110:113], v[234:237], v[0:15]
	s_waitcnt lgkmcnt(0)
; #define LAS __attribute__((address_space(3)))
; DI void indexer_tile(const LAS unsigned char* buf, const f16x8 (&af)[2][8], const f32x4 (&wv)[2][4], float* sc0, float* sc1, int kt, int r32, int h2) {
;     ...
;     for (int sub = 0; sub < 2; ++sub) {
;         f32x16 c0, c1;
; #pragma unroll
;         for (int i = 0; i < 16; ++i) { c0[i] = 0.f; c1[i] = 0.f; }
; #pragma unroll
;         for (int ks = 0; ks < 8; ++ks) { c0 = __builtin_amdgcn_mfma_f32_32x32x16_f16(af[0][ks], bfr[sub][ks], c0, 0, 0, 0); c1 = __builtin_amdgcn_mfma_f32_32x32x16_f16(af[1][ks], bfr[sub][ks], c1, 0, 0, 0); }
;         f32x2_t a0 = {0.f, 0.f}, a1 = {0.f, 0.f};
; #pragma unroll
;         for (int q = 0; q < 4; ++q)
; #pragma unroll
;             for (int e = 0; e < 4; e += 2) {
;                 const f32x2_t r0 = {relu1(c0[4 * q + e]), relu1(c0[4 * q + e + 1])};
;                 const f32x2_t r1 = {relu1(c1[4 * q + e]), relu1(c1[4 * q + e + 1])};
;                 const f32x2_t w0 = {wv[0][q][e], wv[0][q][e + 1]}, w1 = {wv[1][q][e], wv[1][q][e + 1]};
;                 a0 = __builtin_elementwise_fma(r0, w0, a0); a1 = __builtin_elementwise_fma(r1, w1, a1); }
;         float s0 = a0.x + a0.y, s1 = a1.x + a1.y;
;         s0 += __shfl_xor(s0, 32); s1 += __shfl_xor(s1, 32);
;         if (h2 == 0) { sc0[kt * 64 + 32 * sub + r32] = s0; sc1[kt * 64 + 32 * sub + r32] = s1; }
; DI void indexer_phase(const unsigned short* QI, const unsigned short* KI16, const float* WI, float* SC, LAS unsigned char* lds, int tid, int bid, int G) {
;     ...
;                 if (kt + 2 < nt) { *(LAS u32x4*)(buf0 + key0 * KT_ROWB + ch * 16) = a0; *(LAS u32x4*)(buf0 + (key0 + 32) * KT_ROWB + ch * 16) = a1; }
	v_mfma_f32_32x32x16_f16 v[16:31], v[34:37], v[174:177], 0
	v_mfma_f32_32x32x16_f16 v[16:31], v[38:41], v[170:173], v[16:31]
	v_mfma_f32_32x32x16_f16 v[16:31], v[42:45], v[166:169], v[16:31]
	s_nop 8
	v_max_i32_e32 v0, 0, v0
	v_max_i32_e32 v1, 0, v1
	v_fma_f32 v240, v0, v114, 0
	v_fma_f32 v241, v1, v115, 0
	v_max_i32_e32 v2, 0, v2
	v_max_i32_e32 v3, 0, v3
	v_fma_f32 v240, v2, v116, v240
	v_mfma_f32_32x32x16_f16 v[16:31], v[46:49], v[162:165], v[16:31]
	v_fma_f32 v241, v3, v117, v241
	v_max_i32_e32 v4, 0, v4
	v_max_i32_e32 v5, 0, v5
	v_fma_f32 v240, v4, v118, v240
	v_fma_f32 v241, v5, v119, v241
	v_max_i32_e32 v6, 0, v6
	v_max_i32_e32 v7, 0, v7
	v_mfma_f32_32x32x16_f16 v[16:31], v[50:53], v[158:161], v[16:31]
	v_fma_f32 v240, v6, v120, v240
	v_fma_f32 v241, v7, v121, v241
	v_max_i32_e32 v8, 0, v8
	v_max_i32_e32 v9, 0, v9
	v_fma_f32 v240, v8, v122, v240
	v_fma_f32 v241, v9, v123, v241
	v_mfma_f32_32x32x16_f16 v[16:31], v[54:57], v[154:157], v[16:31]
	v_max_i32_e32 v10, 0, v10
	v_max_i32_e32 v11, 0, v11
	v_fma_f32 v240, v10, v124, v240
	v_fma_f32 v241, v11, v125, v241
	v_max_i32_e32 v12, 0, v12
	v_max_i32_e32 v13, 0, v13
	v_mfma_f32_32x32x16_f16 v[16:31], v[58:61], v[150:153], v[16:31]
	v_fma_f32 v240, v12, v126, v240
	v_fma_f32 v241, v13, v127, v241
	v_max_i32_e32 v14, 0, v14
	v_max_i32_e32 v15, 0, v15
	v_fma_f32 v240, v14, v128, v240
	v_fma_f32 v241, v15, v129, v241
	v_mfma_f32_32x32x16_f16 v[16:31], v[62:65], v[146:149], v[16:31]
	v_add_f32_e32 v242, v238, v239
	v_add_f32_e32 v243, v240, v241
	v_lshl_add_u32 v244, v32, 2, v248
	s_nop 0
	v_permlane32_swap_b32_e32 v242, v243
	v_add_f32_e32 v242, v242, v243
	global_store_dword v244, v242, s[24:25] offset:256
	v_mfma_f32_32x32x16_f16 v[0:15], v[82:85], v[174:177], 0
	v_mfma_f32_32x32x16_f16 v[0:15], v[86:89], v[170:173], v[0:15]
	v_mfma_f32_32x32x16_f16 v[0:15], v[90:93], v[166:169], v[0:15]
	s_nop 8
	v_max_i32_e32 v16, 0, v16
	v_max_i32_e32 v17, 0, v17
	v_fma_f32 v238, v16, v66, 0
	v_fma_f32 v239, v17, v67, 0
	v_max_i32_e32 v18, 0, v18
	v_max_i32_e32 v19, 0, v19
	v_fma_f32 v238, v18, v68, v238
	v_mfma_f32_32x32x16_f16 v[0:15], v[94:97], v[162:165], v[0:15]
	v_fma_f32 v239, v19, v69, v239
	v_max_i32_e32 v20, 0, v20
	v_max_i32_e32 v21, 0, v21
	v_fma_f32 v238, v20, v70, v238
	v_fma_f32 v239, v21, v71, v239
	v_max_i32_e32 v22, 0, v22
	v_max_i32_e32 v23, 0, v23
	v_mfma_f32_32x32x16_f16 v[0:15], v[98:101], v[158:161], v[0:15]
	v_fma_f32 v238, v22, v72, v238
	v_fma_f32 v239, v23, v73, v239
	v_max_i32_e32 v24, 0, v24
	v_max_i32_e32 v25, 0, v25
	v_fma_f32 v238, v24, v74, v238
	v_fma_f32 v239, v25, v75, v239
	v_mfma_f32_32x32x16_f16 v[0:15], v[102:105], v[154:157], v[0:15]
	v_max_i32_e32 v26, 0, v26
	v_max_i32_e32 v27, 0, v27
	v_fma_f32 v238, v26, v76, v238
	v_fma_f32 v239, v27, v77, v239
	v_max_i32_e32 v28, 0, v28
	v_max_i32_e32 v29, 0, v29
	v_mfma_f32_32x32x16_f16 v[0:15], v[106:109], v[150:153], v[0:15]
	v_fma_f32 v238, v28, v78, v238
	v_fma_f32 v239, v29, v79, v239
	v_max_i32_e32 v30, 0, v30
	v_max_i32_e32 v31, 0, v31
	v_fma_f32 v238, v30, v80, v238
	v_fma_f32 v239, v31, v81, v239
	v_mfma_f32_32x32x16_f16 v[0:15], v[110:113], v[146:149], v[0:15]
	s_nop 11
	v_max_i32_e32 v0, 0, v0
	v_max_i32_e32 v1, 0, v1
	v_fma_f32 v240, v0, v114, 0
	v_fma_f32 v241, v1, v115, 0
	v_max_i32_e32 v2, 0, v2
	v_max_i32_e32 v3, 0, v3
	v_fma_f32 v240, v2, v116, v240
	v_fma_f32 v241, v3, v117, v241
	v_max_i32_e32 v4, 0, v4
	v_max_i32_e32 v5, 0, v5
	v_fma_f32 v240, v4, v118, v240
	v_fma_f32 v241, v5, v119, v241
	v_max_i32_e32 v6, 0, v6
	v_max_i32_e32 v7, 0, v7
	v_fma_f32 v240, v6, v120, v240
	v_fma_f32 v241, v7, v121, v241
	v_max_i32_e32 v8, 0, v8
	v_max_i32_e32 v9, 0, v9
	v_fma_f32 v240, v8, v122, v240
	v_fma_f32 v241, v9, v123, v241
	v_max_i32_e32 v10, 0, v10
	v_max_i32_e32 v11, 0, v11
	v_fma_f32 v240, v10, v124, v240
	v_fma_f32 v241, v11, v125, v241
	v_max_i32_e32 v12, 0, v12
	v_max_i32_e32 v13, 0, v13
	v_fma_f32 v240, v12, v126, v240
	v_fma_f32 v241, v13, v127, v241
	v_max_i32_e32 v14, 0, v14
	v_max_i32_e32 v15, 0, v15
	v_fma_f32 v240, v14, v128, v240
	v_fma_f32 v241, v15, v129, v241
	v_add_f32_e32 v242, v238, v239
	v_add_f32_e32 v243, v240, v241
	v_lshl_add_u32 v244, v32, 2, v248
	s_nop 0
	v_permlane32_swap_b32_e32 v242, v243
	v_add_f32_e32 v242, v242, v243
	global_store_dword v244, v242, s[24:25] offset:384
	s_andn2_b64 vcc, exec, s[28:29]
	s_cbranch_vccnz .LBB0_1844
	s_waitcnt vmcnt(4)
	ds_write_b128 v209, v[130:133]
	ds_write_b128 v209, v[138:141] offset:8704
	s_branch .LBB0_1844

; #define LAS __attribute__((address_space(3)))
; DI size_t sc_row_off(int b, int s) { const int qb = s >> 7; return ((size_t)(b * 2080 + ((qb * (qb + 1)) >> 1))) * 16384 + (size_t)(s & 127) * ((qb + 1) * 128); }
; DI void indexer_phase(const unsigned short* QI, const unsigned short* KI16, const float* WI, float* SC, LAS unsigned char* lds, int tid, int bid, int G) {
;     ...
;             float* sc0 = SC + sc_row_off(b, tb + 2 * w); float* sc1 = SC + sc_row_off(b, tb + 2 * w + 1);
;             const unsigned short* src = KI16 + (size_t)b * SEQ * 128 + (size_t)key0 * 128 + ch * 8;
;             u32x4 a0, a1, b0 = {0u, 0u, 0u, 0u}, b1 = {0u, 0u, 0u, 0u};
;             a0 = *(const u32x4*)src; a1 = *(const u32x4*)(src + 32 * 128);
;             if (nt > 1) { b0 = *(const u32x4*)(src + 64 * 128); b1 = *(const u32x4*)(src + 96 * 128); }
;             __syncthreads();
;             *(LAS u32x4*)(buf0 + key0 * KT_ROWB + ch * 16) = a0; *(LAS u32x4*)(buf0 + (key0 + 32) * KT_ROWB + ch * 16) = a1;
;             __syncthreads();
;             for (int kt = 0; kt < nt; kt += 2) {
.LBB0_1866:
	s_andn2_b64 vcc, exec, s[14:15]
	s_barrier
	s_waitcnt vmcnt(1)
	ds_write_b128 v209, v[132:135]
	s_waitcnt vmcnt(0)
	ds_write_b128 v209, v[136:139] offset:8704
	s_waitcnt lgkmcnt(0)
	s_barrier
	s_cbranch_vccnz .LBB0_1887
	s_ashr_i32 s11, s10, 31
	s_lshl_b64 s[10:11], s[10:11], 16
	s_add_u32 s10, s17, s10
	s_addc_u32 s11, s33, s11
	s_add_u32 s10, s10, 0x8200000
	s_addc_u32 s11, s11, 0
	s_lshl_b64 s[6:7], s[6:7], 2
	s_add_u32 s6, s10, s6
	s_addc_u32 s7, s11, s7
	s_lshl_b64 s[8:9], s[8:9], 2
	s_add_u32 s8, s10, s8
	s_addc_u32 s9, s11, s9
	s_mov_b32 s14, 3
	v_mov_b32_e32 v32, v206
	v_mov_b64_e32 v[34:35], v[202:203]
	s_sub_u32 s98, s8, s6
	v_mov_b32_e32 v248, s98
	s_nop 0
	v_cndmask_b32_e64 v248, v248, 0, s[4:5]
	s_branch .LBB0_1869

; #define LAS __attribute__((address_space(3)))
; DI void indexer_tile(const LAS unsigned char* buf, const f16x8 (&af)[2][8], const f32x4 (&wv)[2][4], float* sc0, float* sc1, int kt, int r32, int h2) {
;     typedef float f32x2_t __attribute__((ext_vector_type(2)));
;     f16x8 bfr[2][8];
; #pragma unroll
;     for (int sub = 0; sub < 2; ++sub)
; #pragma unroll
;         for (int ks = 0; ks < 8; ++ks) bfr[sub][ks] = *(const LAS f16x8*)(buf + (32 * sub + r32) * KT_ROWB + (16 * ks + 8 * h2) * 2);
;     __builtin_amdgcn_sched_barrier(0);
; #pragma unroll
;     for (int sub = 0; sub < 2; ++sub) {
;         f32x16 c0, c1;
; #pragma unroll
;         for (int i = 0; i < 16; ++i) { c0[i] = 0.f; c1[i] = 0.f; }
; #pragma unroll
;         for (int ks = 0; ks < 8; ++ks) { c0 = __builtin_amdgcn_mfma_f32_32x32x16_f16(af[0][ks], bfr[sub][ks], c0, 0, 0, 0); c1 = __builtin_amdgcn_mfma_f32_32x32x16_f16(af[1][ks], bfr[sub][ks], c1, 0, 0, 0); }
;         f32x2_t a0 = {0.f, 0.f}, a1 = {0.f, 0.f};
; #pragma unroll
;         for (int q = 0; q < 4; ++q)
; #pragma unroll
;             for (int e = 0; e < 4; e += 2) {
;                 const f32x2_t r0 = {relu1(c0[4 * q + e]), relu1(c0[4 * q + e + 1])};
;                 const f32x2_t r1 = {relu1(c1[4 * q + e]), relu1(c1[4 * q + e + 1])};
;                 const f32x2_t w0 = {wv[0][q][e], wv[0][q][e + 1]}, w1 = {wv[1][q][e], wv[1][q][e + 1]};
;                 a0 = __builtin_elementwise_fma(r0, w0, a0); a1 = __builtin_elementwise_fma(r1, w1, a1); }
;         float s0 = a0.x + a0.y, s1 = a1.x + a1.y;
;         s0 += __shfl_xor(s0, 32); s1 += __shfl_xor(s1, 32);
;         if (h2 == 0) { sc0[kt * 64 + 32 * sub + r32] = s0; sc1[kt * 64 + 32 * sub + r32] = s1; }
.LBB0_1871:
	ds_read_b128 v[0:3], v207
	ds_read_b128 v[210:213], v207 offset:32
	ds_read_b128 v[214:217], v207 offset:64
	ds_read_b128 v[218:221], v207 offset:96
	ds_read_b128 v[222:225], v207 offset:128
	ds_read_b128 v[226:229], v207 offset:160
	ds_read_b128 v[230:233], v207 offset:192
	ds_read_b128 v[234:237], v207 offset:224
	ds_read_b128 v[176:179], v207 offset:8704
	ds_read_b128 v[172:175], v207 offset:8736
	ds_read_b128 v[168:171], v207 offset:8768
	ds_read_b128 v[164:167], v207 offset:8800
	ds_read_b128 v[160:163], v207 offset:8832
	ds_read_b128 v[156:159], v207 offset:8864
	ds_read_b128 v[152:155], v207 offset:8896
	ds_read_b128 v[148:151], v207 offset:8928
	s_waitcnt lgkmcnt(15)
	v_mfma_f32_32x32x16_f16 v[16:31], v[36:39], v[0:3], 0
	s_waitcnt lgkmcnt(14)
	v_mfma_f32_32x32x16_f16 v[16:31], v[40:43], v[210:213], v[16:31]
	s_waitcnt lgkmcnt(13)
	v_mfma_f32_32x32x16_f16 v[16:31], v[44:47], v[214:217], v[16:31]
	s_waitcnt lgkmcnt(12)
	v_mfma_f32_32x32x16_f16 v[16:31], v[48:51], v[218:221], v[16:31]
	s_waitcnt lgkmcnt(11)
	v_mfma_f32_32x32x16_f16 v[16:31], v[52:55], v[222:225], v[16:31]
	s_waitcnt lgkmcnt(10)
	v_mfma_f32_32x32x16_f16 v[16:31], v[56:59], v[226:229], v[16:31]
	s_waitcnt lgkmcnt(9)
	v_mfma_f32_32x32x16_f16 v[16:31], v[60:63], v[230:233], v[16:31]
	s_waitcnt lgkmcnt(8)
	v_mfma_f32_32x32x16_f16 v[16:31], v[64:67], v[234:237], v[16:31]
	v_mfma_f32_32x32x16_f16 v[0:15], v[84:87], v[0:3], 0
	v_mfma_f32_32x32x16_f16 v[0:15], v[88:91], v[210:213], v[0:15]
	v_mfma_f32_32x32x16_f16 v[0:15], v[92:95], v[214:217], v[0:15]
	s_nop 8
	v_max_i32_e32 v16, 0, v16
	v_max_i32_e32 v17, 0, v17
	v_fma_f32 v238, v16, v68, 0
	v_fma_f32 v239, v17, v69, 0
	v_max_i32_e32 v18, 0, v18
	v_max_i32_e32 v19, 0, v19
	v_fma_f32 v238, v18, v70, v238
	v_mfma_f32_32x32x16_f16 v[0:15], v[96:99], v[218:221], v[0:15]
	v_fma_f32 v239, v19, v71, v239
	v_max_i32_e32 v20, 0, v20
	v_max_i32_e32 v21, 0, v21
	v_fma_f32 v238, v20, v72, v238
	v_fma_f32 v239, v21, v73, v239
	v_max_i32_e32 v22, 0, v22
	v_max_i32_e32 v23, 0, v23
	v_mfma_f32_32x32x16_f16 v[0:15], v[100:103], v[222:225], v[0:15]
	v_fma_f32 v238, v22, v74, v238
	v_fma_f32 v239, v23, v75, v239
	v_max_i32_e32 v24, 0, v24
	v_max_i32_e32 v25, 0, v25
	v_fma_f32 v238, v24, v76, v238
	v_fma_f32 v239, v25, v77, v239
	v_mfma_f32_32x32x16_f16 v[0:15], v[104:107], v[226:229], v[0:15]
	v_max_i32_e32 v26, 0, v26
	v_max_i32_e32 v27, 0, v27
	v_fma_f32 v238, v26, v78, v238
	v_fma_f32 v239, v27, v79, v239
	v_max_i32_e32 v28, 0, v28
	v_max_i32_e32 v29, 0, v29
	v_mfma_f32_32x32x16_f16 v[0:15], v[108:111], v[230:233], v[0:15]
	v_fma_f32 v238, v28, v80, v238
	v_fma_f32 v239, v29, v81, v239
	v_max_i32_e32 v30, 0, v30
	v_max_i32_e32 v31, 0, v31
	v_fma_f32 v238, v30, v82, v238
	v_fma_f32 v239, v31, v83, v239
	v_mfma_f32_32x32x16_f16 v[0:15], v[112:115], v[234:237], v[0:15]
	s_waitcnt lgkmcnt(0)
; #define LAS __attribute__((address_space(3)))
; DI void indexer_tile(const LAS unsigned char* buf, const f16x8 (&af)[2][8], const f32x4 (&wv)[2][4], float* sc0, float* sc1, int kt, int r32, int h2) {
;     ...
;     for (int sub = 0; sub < 2; ++sub) {
;         f32x16 c0, c1;
; #pragma unroll
;         for (int i = 0; i < 16; ++i) { c0[i] = 0.f; c1[i] = 0.f; }
; #pragma unroll
;         for (int ks = 0; ks < 8; ++ks) { c0 = __builtin_amdgcn_mfma_f32_32x32x16_f16(af[0][ks], bfr[sub][ks], c0, 0, 0, 0); c1 = __builtin_amdgcn_mfma_f32_32x32x16_f16(af[1][ks], bfr[sub][ks], c1, 0, 0, 0); }
;         f32x2_t a0 = {0.f, 0.f}, a1 = {0.f, 0.f};
; #pragma unroll
;         for (int q = 0; q < 4; ++q)
; #pragma unroll
;             for (int e = 0; e < 4; e += 2) {
;                 const f32x2_t r0 = {relu1(c0[4 * q + e]), relu1(c0[4 * q + e + 1])};
;                 const f32x2_t r1 = {relu1(c1[4 * q + e]), relu1(c1[4 * q + e + 1])};
;                 const f32x2_t w0 = {wv[0][q][e], wv[0][q][e + 1]}, w1 = {wv[1][q][e], wv[1][q][e + 1]};
;                 a0 = __builtin_elementwise_fma(r0, w0, a0); a1 = __builtin_elementwise_fma(r1, w1, a1); }
;         float s0 = a0.x + a0.y, s1 = a1.x + a1.y;
;         s0 += __shfl_xor(s0, 32); s1 += __shfl_xor(s1, 32);
;         if (h2 == 0) { sc0[kt * 64 + 32 * sub + r32] = s0; sc1[kt * 64 + 32 * sub + r32] = s1; }
; DI void indexer_phase(const unsigned short* QI, const unsigned short* KI16, const float* WI, float* SC, LAS unsigned char* lds, int tid, int bid, int G) {
;     ...
;                 if (kt + 1 < nt) { *(LAS u32x4*)(buf1 + key0 * KT_ROWB + ch * 16) = b0; *(LAS u32x4*)(buf1 + (key0 + 32) * KT_ROWB + ch * 16) = b1; }
;                 __syncthreads();
;                 if (kt + 1 >= nt) break;
	v_mfma_f32_32x32x16_f16 v[16:31], v[36:39], v[176:179], 0
	v_mfma_f32_32x32x16_f16 v[16:31], v[40:43], v[172:175], v[16:31]
	v_mfma_f32_32x32x16_f16 v[16:31], v[44:47], v[168:171], v[16:31]
	s_nop 8
	v_max_i32_e32 v0, 0, v0
	v_max_i32_e32 v1, 0, v1
	v_fma_f32 v240, v0, v116, 0
	v_fma_f32 v241, v1, v117, 0
	v_max_i32_e32 v2, 0, v2
	v_max_i32_e32 v3, 0, v3
	v_fma_f32 v240, v2, v118, v240
	v_mfma_f32_32x32x16_f16 v[16:31], v[48:51], v[164:167], v[16:31]
	v_fma_f32 v241, v3, v119, v241
	v_max_i32_e32 v4, 0, v4
	v_max_i32_e32 v5, 0, v5
	v_fma_f32 v240, v4, v120, v240
	v_fma_f32 v241, v5, v121, v241
	v_max_i32_e32 v6, 0, v6
	v_max_i32_e32 v7, 0, v7
	v_mfma_f32_32x32x16_f16 v[16:31], v[52:55], v[160:163], v[16:31]
	v_fma_f32 v240, v6, v122, v240
	v_fma_f32 v241, v7, v123, v241
	v_max_i32_e32 v8, 0, v8
	v_max_i32_e32 v9, 0, v9
	v_fma_f32 v240, v8, v124, v240
	v_fma_f32 v241, v9, v125, v241
	v_mfma_f32_32x32x16_f16 v[16:31], v[56:59], v[156:159], v[16:31]
	v_max_i32_e32 v10, 0, v10
	v_max_i32_e32 v11, 0, v11
	v_fma_f32 v240, v10, v126, v240
	v_fma_f32 v241, v11, v127, v241
	v_max_i32_e32 v12, 0, v12
	v_max_i32_e32 v13, 0, v13
	v_mfma_f32_32x32x16_f16 v[16:31], v[60:63], v[152:155], v[16:31]
	v_fma_f32 v240, v12, v128, v240
	v_fma_f32 v241, v13, v129, v241
	v_max_i32_e32 v14, 0, v14
	v_max_i32_e32 v15, 0, v15
	v_fma_f32 v240, v14, v130, v240
	v_fma_f32 v241, v15, v131, v241
	v_mfma_f32_32x32x16_f16 v[16:31], v[64:67], v[148:151], v[16:31]
	v_add_f32_e32 v242, v238, v239
	v_add_f32_e32 v243, v240, v241
	v_lshl_add_u32 v244, v32, 2, v248
	s_nop 0
	v_permlane32_swap_b32_e32 v242, v243
	v_add_f32_e32 v242, v242, v243
	global_store_dword v244, v242, s[6:7]
	v_mfma_f32_32x32x16_f16 v[0:15], v[84:87], v[176:179], 0
	v_mfma_f32_32x32x16_f16 v[0:15], v[88:91], v[172:175], v[0:15]
	v_mfma_f32_32x32x16_f16 v[0:15], v[92:95], v[168:171], v[0:15]
	s_nop 8
	v_max_i32_e32 v16, 0, v16
	v_max_i32_e32 v17, 0, v17
	v_fma_f32 v238, v16, v68, 0
	v_fma_f32 v239, v17, v69, 0
	v_max_i32_e32 v18, 0, v18
	v_max_i32_e32 v19, 0, v19
	v_fma_f32 v238, v18, v70, v238
	v_mfma_f32_32x32x16_f16 v[0:15], v[96:99], v[164:167], v[0:15]
	v_fma_f32 v239, v19, v71, v239
	v_max_i32_e32 v20, 0, v20
	v_max_i32_e32 v21, 0, v21
	v_fma_f32 v238, v20, v72, v238
	v_fma_f32 v239, v21, v73, v239
	v_max_i32_e32 v22, 0, v22
	v_max_i32_e32 v23, 0, v23
	v_mfma_f32_32x32x16_f16 v[0:15], v[100:103], v[160:163], v[0:15]
	v_fma_f32 v238, v22, v74, v238
	v_fma_f32 v239, v23, v75, v239
	v_max_i32_e32 v24, 0, v24
	v_max_i32_e32 v25, 0, v25
	v_fma_f32 v238, v24, v76, v238
	v_fma_f32 v239, v25, v77, v239
	v_mfma_f32_32x32x16_f16 v[0:15], v[104:107], v[156:159], v[0:15]
	v_max_i32_e32 v26, 0, v26
	v_max_i32_e32 v27, 0, v27
	v_fma_f32 v238, v26, v78, v238
	v_fma_f32 v239, v27, v79, v239
	v_max_i32_e32 v28, 0, v28
	v_max_i32_e32 v29, 0, v29
	v_mfma_f32_32x32x16_f16 v[0:15], v[108:111], v[152:155], v[0:15]
	v_fma_f32 v238, v28, v80, v238
	v_fma_f32 v239, v29, v81, v239
	v_max_i32_e32 v30, 0, v30
	v_max_i32_e32 v31, 0, v31
	v_fma_f32 v238, v30, v82, v238
	v_fma_f32 v239, v31, v83, v239
	v_mfma_f32_32x32x16_f16 v[0:15], v[112:115], v[148:151], v[0:15]
	s_nop 11
	v_max_i32_e32 v0, 0, v0
	v_max_i32_e32 v1, 0, v1
	v_fma_f32 v240, v0, v116, 0
	v_fma_f32 v241, v1, v117, 0
	v_max_i32_e32 v2, 0, v2
	v_max_i32_e32 v3, 0, v3
	v_fma_f32 v240, v2, v118, v240
	v_fma_f32 v241, v3, v119, v241
	v_max_i32_e32 v4, 0, v4
	v_max_i32_e32 v5, 0, v5
	v_fma_f32 v240, v4, v120, v240
	v_fma_f32 v241, v5, v121, v241
	v_max_i32_e32 v6, 0, v6
	v_max_i32_e32 v7, 0, v7
	v_fma_f32 v240, v6, v122, v240
	v_fma_f32 v241, v7, v123, v241
	v_max_i32_e32 v8, 0, v8
	v_max_i32_e32 v9, 0, v9
	v_fma_f32 v240, v8, v124, v240
	v_fma_f32 v241, v9, v125, v241
	v_max_i32_e32 v10, 0, v10
	v_max_i32_e32 v11, 0, v11
	v_fma_f32 v240, v10, v126, v240
	v_fma_f32 v241, v11, v127, v241
	v_max_i32_e32 v12, 0, v12
	v_max_i32_e32 v13, 0, v13
	v_fma_f32 v240, v12, v128, v240
	v_fma_f32 v241, v13, v129, v241
	v_max_i32_e32 v14, 0, v14
	v_max_i32_e32 v15, 0, v15
	v_fma_f32 v240, v14, v130, v240
	v_fma_f32 v241, v15, v131, v241
	v_add_f32_e32 v242, v238, v239
	v_add_f32_e32 v243, v240, v241
	v_lshl_add_u32 v244, v32, 2, v248
	s_nop 0
	v_permlane32_swap_b32_e32 v242, v243
	v_add_f32_e32 v242, v242, v243
	global_store_dword v244, v242, s[6:7] offset:128
	s_add_i32 s24, s14, -3
	s_cmp_lt_i32 s24, s41
	s_cselect_b64 s[12:13], -1, 0
	s_cmp_ge_i32 s24, s41
	s_cbranch_scc1 .LBB0_1877
	s_waitcnt vmcnt(4)
	ds_write_b128 v209, v[140:143] offset:17408
	ds_write_b128 v209, v[144:147] offset:26112

; #define LAS __attribute__((address_space(3)))
; DI void indexer_tile(const LAS unsigned char* buf, const f16x8 (&af)[2][8], const f32x4 (&wv)[2][4], float* sc0, float* sc1, int kt, int r32, int h2) {
;     typedef float f32x2_t __attribute__((ext_vector_type(2)));
;     f16x8 bfr[2][8];
; #pragma unroll
;     for (int sub = 0; sub < 2; ++sub)
; #pragma unroll
;         for (int ks = 0; ks < 8; ++ks) bfr[sub][ks] = *(const LAS f16x8*)(buf + (32 * sub + r32) * KT_ROWB + (16 * ks + 8 * h2) * 2);
;     __builtin_amdgcn_sched_barrier(0);
; #pragma unroll
;     for (int sub = 0; sub < 2; ++sub) {
;         f32x16 c0, c1;
; #pragma unroll
;         for (int i = 0; i < 16; ++i) { c0[i] = 0.f; c1[i] = 0.f; }
; #pragma unroll
;         for (int ks = 0; ks < 8; ++ks) { c0 = __builtin_amdgcn_mfma_f32_32x32x16_f16(af[0][ks], bfr[sub][ks], c0, 0, 0, 0); c1 = __builtin_amdgcn_mfma_f32_32x32x16_f16(af[1][ks], bfr[sub][ks], c1, 0, 0, 0); }
;         f32x2_t a0 = {0.f, 0.f}, a1 = {0.f, 0.f};
; #pragma unroll
;         for (int q = 0; q < 4; ++q)
; #pragma unroll
;             for (int e = 0; e < 4; e += 2) {
;                 const f32x2_t r0 = {relu1(c0[4 * q + e]), relu1(c0[4 * q + e + 1])};
;                 const f32x2_t r1 = {relu1(c1[4 * q + e]), relu1(c1[4 * q + e + 1])};
;                 const f32x2_t w0 = {wv[0][q][e], wv[0][q][e + 1]}, w1 = {wv[1][q][e], wv[1][q][e + 1]};
;                 a0 = __builtin_elementwise_fma(r0, w0, a0); a1 = __builtin_elementwise_fma(r1, w1, a1); }
;         float s0 = a0.x + a0.y, s1 = a1.x + a1.y;
;         s0 += __shfl_xor(s0, 32); s1 += __shfl_xor(s1, 32);
;         if (h2 == 0) { sc0[kt * 64 + 32 * sub + r32] = s0; sc1[kt * 64 + 32 * sub + r32] = s1; }
.LBB0_1880:
	ds_read_b128 v[0:3], v207 offset:17408
	ds_read_b128 v[210:213], v207 offset:17440
	ds_read_b128 v[214:217], v207 offset:17472
	ds_read_b128 v[218:221], v207 offset:17504
	ds_read_b128 v[222:225], v207 offset:17536
	ds_read_b128 v[226:229], v207 offset:17568
	ds_read_b128 v[230:233], v207 offset:17600
	ds_read_b128 v[234:237], v207 offset:17632
	ds_read_b128 v[176:179], v207 offset:26112
	ds_read_b128 v[172:175], v207 offset:26144
	ds_read_b128 v[168:171], v207 offset:26176
	ds_read_b128 v[164:167], v207 offset:26208
	ds_read_b128 v[160:163], v207 offset:26240
	ds_read_b128 v[156:159], v207 offset:26272
	ds_read_b128 v[152:155], v207 offset:26304
	ds_read_b128 v[148:151], v207 offset:26336
	s_waitcnt lgkmcnt(15)
	v_mfma_f32_32x32x16_f16 v[16:31], v[36:39], v[0:3], 0
	s_waitcnt lgkmcnt(14)
	v_mfma_f32_32x32x16_f16 v[16:31], v[40:43], v[210:213], v[16:31]
	s_waitcnt lgkmcnt(13)
	v_mfma_f32_32x32x16_f16 v[16:31], v[44:47], v[214:217], v[16:31]
	s_waitcnt lgkmcnt(12)
	v_mfma_f32_32x32x16_f16 v[16:31], v[48:51], v[218:221], v[16:31]
	s_waitcnt lgkmcnt(11)
	v_mfma_f32_32x32x16_f16 v[16:31], v[52:55], v[222:225], v[16:31]
	s_waitcnt lgkmcnt(10)
	v_mfma_f32_32x32x16_f16 v[16:31], v[56:59], v[226:229], v[16:31]
	s_waitcnt lgkmcnt(9)
	v_mfma_f32_32x32x16_f16 v[16:31], v[60:63], v[230:233], v[16:31]
	s_waitcnt lgkmcnt(8)
	v_mfma_f32_32x32x16_f16 v[16:31], v[64:67], v[234:237], v[16:31]
	v_mfma_f32_32x32x16_f16 v[0:15], v[84:87], v[0:3], 0
	v_mfma_f32_32x32x16_f16 v[0:15], v[88:91], v[210:213], v[0:15]
	v_mfma_f32_32x32x16_f16 v[0:15], v[92:95], v[214:217], v[0:15]
	s_nop 8
	v_max_i32_e32 v16, 0, v16
	v_max_i32_e32 v17, 0, v17
	v_fma_f32 v238, v16, v68, 0
	v_fma_f32 v239, v17, v69, 0
	v_max_i32_e32 v18, 0, v18
	v_max_i32_e32 v19, 0, v19
	v_fma_f32 v238, v18, v70, v238
	v_mfma_f32_32x32x16_f16 v[0:15], v[96:99], v[218:221], v[0:15]
	v_fma_f32 v239, v19, v71, v239
	v_max_i32_e32 v20, 0, v20
	v_max_i32_e32 v21, 0, v21
	v_fma_f32 v238, v20, v72, v238
	v_fma_f32 v239, v21, v73, v239
	v_max_i32_e32 v22, 0, v22
	v_max_i32_e32 v23, 0, v23
	v_mfma_f32_32x32x16_f16 v[0:15], v[100:103], v[222:225], v[0:15]
	v_fma_f32 v238, v22, v74, v238
	v_fma_f32 v239, v23, v75, v239
	v_max_i32_e32 v24, 0, v24
	v_max_i32_e32 v25, 0, v25
	v_fma_f32 v238, v24, v76, v238
	v_fma_f32 v239, v25, v77, v239
	v_mfma_f32_32x32x16_f16 v[0:15], v[104:107], v[226:229], v[0:15]
	v_max_i32_e32 v26, 0, v26
	v_max_i32_e32 v27, 0, v27
	v_fma_f32 v238, v26, v78, v238
	v_fma_f32 v239, v27, v79, v239
	v_max_i32_e32 v28, 0, v28
	v_max_i32_e32 v29, 0, v29
	v_mfma_f32_32x32x16_f16 v[0:15], v[108:111], v[230:233], v[0:15]
	v_fma_f32 v238, v28, v80, v238
	v_fma_f32 v239, v29, v81, v239
	v_max_i32_e32 v30, 0, v30
	v_max_i32_e32 v31, 0, v31
	v_fma_f32 v238, v30, v82, v238
	v_fma_f32 v239, v31, v83, v239
	v_mfma_f32_32x32x16_f16 v[0:15], v[112:115], v[234:237], v[0:15]
	s_waitcnt lgkmcnt(0)
; #define LAS __attribute__((address_space(3)))
; DI void indexer_tile(const LAS unsigned char* buf, const f16x8 (&af)[2][8], const f32x4 (&wv)[2][4], float* sc0, float* sc1, int kt, int r32, int h2) {
;     ...
;     for (int sub = 0; sub < 2; ++sub) {
;         f32x16 c0, c1;
; #pragma unroll
;         for (int i = 0; i < 16; ++i) { c0[i] = 0.f; c1[i] = 0.f; }
; #pragma unroll
;         for (int ks = 0; ks < 8; ++ks) { c0 = __builtin_amdgcn_mfma_f32_32x32x16_f16(af[0][ks], bfr[sub][ks], c0, 0, 0, 0); c1 = __builtin_amdgcn_mfma_f32_32x32x16_f16(af[1][ks], bfr[sub][ks], c1, 0, 0, 0); }
;         f32x2_t a0 = {0.f, 0.f}, a1 = {0.f, 0.f};
; #pragma unroll
;         for (int q = 0; q < 4; ++q)
; #pragma unroll
;             for (int e = 0; e < 4; e += 2) {
;                 const f32x2_t r0 = {relu1(c0[4 * q + e]), relu1(c0[4 * q + e + 1])};
;                 const f32x2_t r1 = {relu1(c1[4 * q + e]), relu1(c1[4 * q + e + 1])};
;                 const f32x2_t w0 = {wv[0][q][e], wv[0][q][e + 1]}, w1 = {wv[1][q][e], wv[1][q][e + 1]};
;                 a0 = __builtin_elementwise_fma(r0, w0, a0); a1 = __builtin_elementwise_fma(r1, w1, a1); }
;         float s0 = a0.x + a0.y, s1 = a1.x + a1.y;
;         s0 += __shfl_xor(s0, 32); s1 += __shfl_xor(s1, 32);
;         if (h2 == 0) { sc0[kt * 64 + 32 * sub + r32] = s0; sc1[kt * 64 + 32 * sub + r32] = s1; }
; DI void indexer_phase(const unsigned short* QI, const unsigned short* KI16, const float* WI, float* SC, LAS unsigned char* lds, int tid, int bid, int G) {
;     ...
;                 if (kt + 2 < nt) { *(LAS u32x4*)(buf0 + key0 * KT_ROWB + ch * 16) = a0; *(LAS u32x4*)(buf0 + (key0 + 32) * KT_ROWB + ch * 16) = a1; }
	v_mfma_f32_32x32x16_f16 v[16:31], v[36:39], v[176:179], 0
	v_mfma_f32_32x32x16_f16 v[16:31], v[40:43], v[172:175], v[16:31]
	v_mfma_f32_32x32x16_f16 v[16:31], v[44:47], v[168:171], v[16:31]
	s_nop 8
	v_max_i32_e32 v0, 0, v0
	v_max_i32_e32 v1, 0, v1
	v_fma_f32 v240, v0, v116, 0
	v_fma_f32 v241, v1, v117, 0
	v_max_i32_e32 v2, 0, v2
	v_max_i32_e32 v3, 0, v3
	v_fma_f32 v240, v2, v118, v240
	v_mfma_f32_32x32x16_f16 v[16:31], v[48:51], v[164:167], v[16:31]
	v_fma_f32 v241, v3, v119, v241
	v_max_i32_e32 v4, 0, v4
	v_max_i32_e32 v5, 0, v5
	v_fma_f32 v240, v4, v120, v240
	v_fma_f32 v241, v5, v121, v241
	v_max_i32_e32 v6, 0, v6
	v_max_i32_e32 v7, 0, v7
	v_mfma_f32_32x32x16_f16 v[16:31], v[52:55], v[160:163], v[16:31]
	v_fma_f32 v240, v6, v122, v240
	v_fma_f32 v241, v7, v123, v241
	v_max_i32_e32 v8, 0, v8
	v_max_i32_e32 v9, 0, v9
	v_fma_f32 v240, v8, v124, v240
	v_fma_f32 v241, v9, v125, v241
	v_mfma_f32_32x32x16_f16 v[16:31], v[56:59], v[156:159], v[16:31]
	v_max_i32_e32 v10, 0, v10
	v_max_i32_e32 v11, 0, v11
	v_fma_f32 v240, v10, v126, v240
	v_fma_f32 v241, v11, v127, v241
	v_max_i32_e32 v12, 0, v12
	v_max_i32_e32 v13, 0, v13
	v_mfma_f32_32x32x16_f16 v[16:31], v[60:63], v[152:155], v[16:31]
	v_fma_f32 v240, v12, v128, v240
	v_fma_f32 v241, v13, v129, v241
	v_max_i32_e32 v14, 0, v14
	v_max_i32_e32 v15, 0, v15
	v_fma_f32 v240, v14, v130, v240
	v_fma_f32 v241, v15, v131, v241
	v_mfma_f32_32x32x16_f16 v[16:31], v[64:67], v[148:151], v[16:31]
	v_add_f32_e32 v242, v238, v239
	v_add_f32_e32 v243, v240, v241
	v_lshl_add_u32 v244, v32, 2, v248
	s_nop 0
	v_permlane32_swap_b32_e32 v242, v243
	v_add_f32_e32 v242, v242, v243
	global_store_dword v244, v242, s[6:7] offset:256
	v_mfma_f32_32x32x16_f16 v[0:15], v[84:87], v[176:179], 0
	v_mfma_f32_32x32x16_f16 v[0:15], v[88:91], v[172:175], v[0:15]
	v_mfma_f32_32x32x16_f16 v[0:15], v[92:95], v[168:171], v[0:15]
	s_nop 8
	v_max_i32_e32 v16, 0, v16
	v_max_i32_e32 v17, 0, v17
	v_fma_f32 v238, v16, v68, 0
	v_fma_f32 v239, v17, v69, 0
	v_max_i32_e32 v18, 0, v18
	v_max_i32_e32 v19, 0, v19
	v_fma_f32 v238, v18, v70, v238
	v_mfma_f32_32x32x16_f16 v[0:15], v[96:99], v[164:167], v[0:15]
	v_fma_f32 v239, v19, v71, v239
	v_max_i32_e32 v20, 0, v20
	v_max_i32_e32 v21, 0, v21
	v_fma_f32 v238, v20, v72, v238
	v_fma_f32 v239, v21, v73, v239
	v_max_i32_e32 v22, 0, v22
	v_max_i32_e32 v23, 0, v23
	v_mfma_f32_32x32x16_f16 v[0:15], v[100:103], v[160:163], v[0:15]
	v_fma_f32 v238, v22, v74, v238
	v_fma_f32 v239, v23, v75, v239
	v_max_i32_e32 v24, 0, v24
	v_max_i32_e32 v25, 0, v25
	v_fma_f32 v238, v24, v76, v238
	v_fma_f32 v239, v25, v77, v239
	v_mfma_f32_32x32x16_f16 v[0:15], v[104:107], v[156:159], v[0:15]
	v_max_i32_e32 v26, 0, v26
	v_max_i32_e32 v27, 0, v27
	v_fma_f32 v238, v26, v78, v238
	v_fma_f32 v239, v27, v79, v239
	v_max_i32_e32 v28, 0, v28
	v_max_i32_e32 v29, 0, v29
	v_mfma_f32_32x32x16_f16 v[0:15], v[108:111], v[152:155], v[0:15]
	v_fma_f32 v238, v28, v80, v238
	v_fma_f32 v239, v29, v81, v239
	v_max_i32_e32 v30, 0, v30
	v_max_i32_e32 v31, 0, v31
	v_fma_f32 v238, v30, v82, v238
	v_fma_f32 v239, v31, v83, v239
	v_mfma_f32_32x32x16_f16 v[0:15], v[112:115], v[148:151], v[0:15]
	s_nop 11
	v_max_i32_e32 v0, 0, v0
	v_max_i32_e32 v1, 0, v1
	v_fma_f32 v240, v0, v116, 0
	v_fma_f32 v241, v1, v117, 0
	v_max_i32_e32 v2, 0, v2
	v_max_i32_e32 v3, 0, v3
	v_fma_f32 v240, v2, v118, v240
	v_fma_f32 v241, v3, v119, v241
	v_max_i32_e32 v4, 0, v4
	v_max_i32_e32 v5, 0, v5
	v_fma_f32 v240, v4, v120, v240
	v_fma_f32 v241, v5, v121, v241
	v_max_i32_e32 v6, 0, v6
	v_max_i32_e32 v7, 0, v7
	v_fma_f32 v240, v6, v122, v240
	v_fma_f32 v241, v7, v123, v241
	v_max_i32_e32 v8, 0, v8
	v_max_i32_e32 v9, 0, v9
	v_fma_f32 v240, v8, v124, v240
	v_fma_f32 v241, v9, v125, v241
	v_max_i32_e32 v10, 0, v10
	v_max_i32_e32 v11, 0, v11
	v_fma_f32 v240, v10, v126, v240
	v_fma_f32 v241, v11, v127, v241
	v_max_i32_e32 v12, 0, v12
	v_max_i32_e32 v13, 0, v13
	v_fma_f32 v240, v12, v128, v240
	v_fma_f32 v241, v13, v129, v241
	v_max_i32_e32 v14, 0, v14
	v_max_i32_e32 v15, 0, v15
	v_fma_f32 v240, v14, v130, v240
	v_fma_f32 v241, v15, v131, v241
	v_add_f32_e32 v242, v238, v239
	v_add_f32_e32 v243, v240, v241
	v_lshl_add_u32 v244, v32, 2, v248
	s_nop 0
	v_permlane32_swap_b32_e32 v242, v243
	v_add_f32_e32 v242, v242, v243
	global_store_dword v244, v242, s[6:7] offset:384
	s_andn2_b64 vcc, exec, s[10:11]
	s_cbranch_vccnz .LBB0_1868
	s_waitcnt vmcnt(4)
	ds_write_b128 v209, v[132:135]
	ds_write_b128 v209, v[136:139] offset:8704
	s_branch .LBB0_1868

; #define LAS __attribute__((address_space(3)))
; DI size_t sc_row_off(int b, int s) { const int qb = s >> 7; return ((size_t)(b * 2080 + ((qb * (qb + 1)) >> 1))) * 16384 + (size_t)(s & 127) * ((qb + 1) * 128); }
; DI void indexer_phase(const unsigned short* QI, const unsigned short* KI16, const float* WI, float* SC, LAS unsigned char* lds, int tid, int bid, int G) {
;     ...
;             const int b = it >> 1, gi = (it & 1) ? (511 - v) : v; const int tb = 16 * gi;
;             const int nt = ((tb + 15) >> 6) + 1;
;             f16x8 af[2][8]; f32x4 wv[2][4];
; #pragma unroll
;             for (int tq = 0; tq < 2; ++tq) { const size_t tg = (size_t)b * SEQ + tb + 2 * w + tq;
; #pragma unroll
;                 for (int ks = 0; ks < 8; ++ks) af[tq][ks] = *(const f16x8*)(QI + tg * 4096 + r32 * 128 + 16 * ks + 8 * h2);
; #pragma unroll
;                 for (int q = 0; q < 4; ++q) wv[tq][q] = *(const f32x4*)(WI + tg * 32 + 8 * q + 4 * h2); }
;             float* sc0 = SC + sc_row_off(b, tb + 2 * w); float* sc1 = SC + sc_row_off(b, tb + 2 * w + 1);
;             const unsigned short* src = KI16 + (size_t)b * SEQ * 128 + (size_t)key0 * 128 + ch * 8;
;             u32x4 a0, a1, b0 = {0u, 0u, 0u, 0u}, b1 = {0u, 0u, 0u, 0u};
;             a0 = *(const u32x4*)src; a1 = *(const u32x4*)(src + 32 * 128);
;             if (nt > 1) { b0 = *(const u32x4*)(src + 64 * 128); b1 = *(const u32x4*)(src + 96 * 128); }
;             __syncthreads();
;             *(LAS u32x4*)(buf0 + key0 * KT_ROWB + ch * 16) = a0; *(LAS u32x4*)(buf0 + (key0 + 32) * KT_ROWB + ch * 16) = a1;
;             __syncthreads();
.LBB0_1887:
	s_add_u32 s6, s38, s45
	s_addc_u32 s7, s39, 0
	s_lshl_b64 s[8:9], s[6:7], 13
	v_lshl_add_u64 v[0:1], v[180:181], 0, s[8:9]
	s_lshl_b64 s[8:9], s[6:7], 7
	s_or_b32 s6, s6, 1
	global_load_dwordx4 v[34:37], v[0:1], off
	global_load_dwordx4 v[38:41], v[0:1], off offset:32
	global_load_dwordx4 v[42:45], v[0:1], off offset:64
	global_load_dwordx4 v[46:49], v[0:1], off offset:96
	global_load_dwordx4 v[50:53], v[0:1], off offset:128
	global_load_dwordx4 v[54:57], v[0:1], off offset:160
	global_load_dwordx4 v[58:61], v[0:1], off offset:192
	global_load_dwordx4 v[62:65], v[0:1], off offset:224
	v_lshl_add_u64 v[0:1], v[182:183], 0, s[8:9]
	s_lshl_b64 s[8:9], s[6:7], 13
	global_load_dwordx4 v[66:69], v[0:1], off
	global_load_dwordx4 v[70:73], v[0:1], off offset:32
	global_load_dwordx4 v[74:77], v[0:1], off offset:64
	global_load_dwordx4 v[78:81], v[0:1], off offset:96
	v_lshl_add_u64 v[0:1], v[180:181], 0, s[8:9]
	global_load_dwordx4 v[82:85], v[0:1], off
	global_load_dwordx4 v[86:89], v[0:1], off offset:32
	global_load_dwordx4 v[90:93], v[0:1], off offset:64
	global_load_dwordx4 v[94:97], v[0:1], off offset:96
	global_load_dwordx4 v[98:101], v[0:1], off offset:128
	global_load_dwordx4 v[102:105], v[0:1], off offset:160
	global_load_dwordx4 v[106:109], v[0:1], off offset:192
	global_load_dwordx4 v[110:113], v[0:1], off offset:224
	s_lshl_b64 s[6:7], s[6:7], 7
	v_lshl_add_u64 v[0:1], v[182:183], 0, s[6:7]
	global_load_dwordx4 v[130:133], v[192:193], off
	global_load_dwordx4 v[138:141], v[194:195], off
	global_load_dwordx4 v[114:117], v[0:1], off
	global_load_dwordx4 v[118:121], v[0:1], off offset:32
	global_load_dwordx4 v[134:137], v[198:199], off
	global_load_dwordx4 v[142:145], v[196:197], off
	global_load_dwordx4 v[122:125], v[0:1], off offset:64
	global_load_dwordx4 v[126:129], v[0:1], off offset:96
	s_lshl_b64 s[6:7], s[18:19], 16
	s_add_u32 s6, s17, s6
	s_addc_u32 s7, s33, s7
	s_add_u32 s8, s6, 0x8200000
	s_addc_u32 s9, s7, 0
	s_add_u32 s6, s8, s20
	s_addc_u32 s7, s9, s21
	s_add_u32 s8, s8, s22
	s_addc_u32 s9, s9, s23
	s_mov_b32 s14, 3
	v_mov_b32_e32 v32, v206
	v_mov_b64_e32 v[178:179], v[202:203]
	s_barrier
	s_waitcnt vmcnt(7)
	ds_write_b128 v209, v[130:133]
	s_waitcnt vmcnt(0)
	ds_write_b128 v209, v[138:141] offset:8704
	s_waitcnt lgkmcnt(0)
	s_barrier
	s_sub_u32 s98, s8, s6
	v_mov_b32_e32 v248, s98
	s_nop 0
	v_cndmask_b32_e64 v248, v248, 0, s[4:5]
	s_branch .LBB0_1889

; #define LAS __attribute__((address_space(3)))
; DI void indexer_tile(const LAS unsigned char* buf, const f16x8 (&af)[2][8], const f32x4 (&wv)[2][4], float* sc0, float* sc1, int kt, int r32, int h2) {
;     typedef float f32x2_t __attribute__((ext_vector_type(2)));
;     f16x8 bfr[2][8];
; #pragma unroll
;     for (int sub = 0; sub < 2; ++sub)
; #pragma unroll
;         for (int ks = 0; ks < 8; ++ks) bfr[sub][ks] = *(const LAS f16x8*)(buf + (32 * sub + r32) * KT_ROWB + (16 * ks + 8 * h2) * 2);
;     __builtin_amdgcn_sched_barrier(0);
; #pragma unroll
;     for (int sub = 0; sub < 2; ++sub) {
;         f32x16 c0, c1;
; #pragma unroll
;         for (int i = 0; i < 16; ++i) { c0[i] = 0.f; c1[i] = 0.f; }
; #pragma unroll
;         for (int ks = 0; ks < 8; ++ks) { c0 = __builtin_amdgcn_mfma_f32_32x32x16_f16(af[0][ks], bfr[sub][ks], c0, 0, 0, 0); c1 = __builtin_amdgcn_mfma_f32_32x32x16_f16(af[1][ks], bfr[sub][ks], c1, 0, 0, 0); }
;         f32x2_t a0 = {0.f, 0.f}, a1 = {0.f, 0.f};
; #pragma unroll
;         for (int q = 0; q < 4; ++q)
; #pragma unroll
;             for (int e = 0; e < 4; e += 2) {
;                 const f32x2_t r0 = {relu1(c0[4 * q + e]), relu1(c0[4 * q + e + 1])};
;                 const f32x2_t r1 = {relu1(c1[4 * q + e]), relu1(c1[4 * q + e + 1])};
;                 const f32x2_t w0 = {wv[0][q][e], wv[0][q][e + 1]}, w1 = {wv[1][q][e], wv[1][q][e + 1]};
;                 a0 = __builtin_elementwise_fma(r0, w0, a0); a1 = __builtin_elementwise_fma(r1, w1, a1); }
;         float s0 = a0.x + a0.y, s1 = a1.x + a1.y;
;         s0 += __shfl_xor(s0, 32); s1 += __shfl_xor(s1, 32);
;         if (h2 == 0) { sc0[kt * 64 + 32 * sub + r32] = s0; sc1[kt * 64 + 32 * sub + r32] = s1; }
.LBB0_1891:
	ds_read_b128 v[0:3], v207
	ds_read_b128 v[210:213], v207 offset:32
	ds_read_b128 v[214:217], v207 offset:64
	ds_read_b128 v[218:221], v207 offset:96
	ds_read_b128 v[222:225], v207 offset:128
	ds_read_b128 v[226:229], v207 offset:160
	ds_read_b128 v[230:233], v207 offset:192
	ds_read_b128 v[234:237], v207 offset:224
	ds_read_b128 v[174:177], v207 offset:8704
	ds_read_b128 v[170:173], v207 offset:8736
	ds_read_b128 v[166:169], v207 offset:8768
	ds_read_b128 v[162:165], v207 offset:8800
	ds_read_b128 v[158:161], v207 offset:8832
	ds_read_b128 v[154:157], v207 offset:8864
	ds_read_b128 v[150:153], v207 offset:8896
	ds_read_b128 v[146:149], v207 offset:8928
	s_waitcnt lgkmcnt(15)
	v_mfma_f32_32x32x16_f16 v[16:31], v[34:37], v[0:3], 0
	s_waitcnt lgkmcnt(14)
	v_mfma_f32_32x32x16_f16 v[16:31], v[38:41], v[210:213], v[16:31]
	s_waitcnt lgkmcnt(13)
	v_mfma_f32_32x32x16_f16 v[16:31], v[42:45], v[214:217], v[16:31]
	s_waitcnt lgkmcnt(12)
	v_mfma_f32_32x32x16_f16 v[16:31], v[46:49], v[218:221], v[16:31]
	s_waitcnt lgkmcnt(11)
	v_mfma_f32_32x32x16_f16 v[16:31], v[50:53], v[222:225], v[16:31]
	s_waitcnt lgkmcnt(10)
	v_mfma_f32_32x32x16_f16 v[16:31], v[54:57], v[226:229], v[16:31]
	s_waitcnt lgkmcnt(9)
	v_mfma_f32_32x32x16_f16 v[16:31], v[58:61], v[230:233], v[16:31]
	s_waitcnt lgkmcnt(8)
	v_mfma_f32_32x32x16_f16 v[16:31], v[62:65], v[234:237], v[16:31]
	v_mfma_f32_32x32x16_f16 v[0:15], v[82:85], v[0:3], 0
	v_mfma_f32_32x32x16_f16 v[0:15], v[86:89], v[210:213], v[0:15]
	v_mfma_f32_32x32x16_f16 v[0:15], v[90:93], v[214:217], v[0:15]
	s_nop 8
	v_max_i32_e32 v16, 0, v16
	v_max_i32_e32 v17, 0, v17
	v_fma_f32 v238, v16, v66, 0
	v_fma_f32 v239, v17, v67, 0
	v_max_i32_e32 v18, 0, v18
	v_max_i32_e32 v19, 0, v19
	v_fma_f32 v238, v18, v68, v238
	v_mfma_f32_32x32x16_f16 v[0:15], v[94:97], v[218:221], v[0:15]
	v_fma_f32 v239, v19, v69, v239
	v_max_i32_e32 v20, 0, v20
	v_max_i32_e32 v21, 0, v21
	v_fma_f32 v238, v20, v70, v238
	v_fma_f32 v239, v21, v71, v239
	v_max_i32_e32 v22, 0, v22
	v_max_i32_e32 v23, 0, v23
	v_mfma_f32_32x32x16_f16 v[0:15], v[98:101], v[222:225], v[0:15]
	v_fma_f32 v238, v22, v72, v238
	v_fma_f32 v239, v23, v73, v239
	v_max_i32_e32 v24, 0, v24
	v_max_i32_e32 v25, 0, v25
	v_fma_f32 v238, v24, v74, v238
	v_fma_f32 v239, v25, v75, v239
	v_mfma_f32_32x32x16_f16 v[0:15], v[102:105], v[226:229], v[0:15]
	v_max_i32_e32 v26, 0, v26
	v_max_i32_e32 v27, 0, v27
	v_fma_f32 v238, v26, v76, v238
	v_fma_f32 v239, v27, v77, v239
	v_max_i32_e32 v28, 0, v28
	v_max_i32_e32 v29, 0, v29
	v_mfma_f32_32x32x16_f16 v[0:15], v[106:109], v[230:233], v[0:15]
	v_fma_f32 v238, v28, v78, v238
	v_fma_f32 v239, v29, v79, v239
	v_max_i32_e32 v30, 0, v30
	v_max_i32_e32 v31, 0, v31
	v_fma_f32 v238, v30, v80, v238
	v_fma_f32 v239, v31, v81, v239
	v_mfma_f32_32x32x16_f16 v[0:15], v[110:113], v[234:237], v[0:15]
	s_waitcnt lgkmcnt(0)
; #define LAS __attribute__((address_space(3)))
; DI void indexer_tile(const LAS unsigned char* buf, const f16x8 (&af)[2][8], const f32x4 (&wv)[2][4], float* sc0, float* sc1, int kt, int r32, int h2) {
;     ...
;     for (int sub = 0; sub < 2; ++sub) {
;         f32x16 c0, c1;
; #pragma unroll
;         for (int i = 0; i < 16; ++i) { c0[i] = 0.f; c1[i] = 0.f; }
; #pragma unroll
;         for (int ks = 0; ks < 8; ++ks) { c0 = __builtin_amdgcn_mfma_f32_32x32x16_f16(af[0][ks], bfr[sub][ks], c0, 0, 0, 0); c1 = __builtin_amdgcn_mfma_f32_32x32x16_f16(af[1][ks], bfr[sub][ks], c1, 0, 0, 0); }
;         f32x2_t a0 = {0.f, 0.f}, a1 = {0.f, 0.f};
; #pragma unroll
;         for (int q = 0; q < 4; ++q)
; #pragma unroll
;             for (int e = 0; e < 4; e += 2) {
;                 const f32x2_t r0 = {relu1(c0[4 * q + e]), relu1(c0[4 * q + e + 1])};
;                 const f32x2_t r1 = {relu1(c1[4 * q + e]), relu1(c1[4 * q + e + 1])};
;                 const f32x2_t w0 = {wv[0][q][e], wv[0][q][e + 1]}, w1 = {wv[1][q][e], wv[1][q][e + 1]};
;                 a0 = __builtin_elementwise_fma(r0, w0, a0); a1 = __builtin_elementwise_fma(r1, w1, a1); }
;         float s0 = a0.x + a0.y, s1 = a1.x + a1.y;
;         s0 += __shfl_xor(s0, 32); s1 += __shfl_xor(s1, 32);
;         if (h2 == 0) { sc0[kt * 64 + 32 * sub + r32] = s0; sc1[kt * 64 + 32 * sub + r32] = s1; }
; DI void indexer_phase(const unsigned short* QI, const unsigned short* KI16, const float* WI, float* SC, LAS unsigned char* lds, int tid, int bid, int G) {
;     ...
;                 if (kt + 1 < nt) { *(LAS u32x4*)(buf1 + key0 * KT_ROWB + ch * 16) = b0; *(LAS u32x4*)(buf1 + (key0 + 32) * KT_ROWB + ch * 16) = b1; }
;                 __syncthreads();
;                 if (kt + 1 >= nt) break;
	v_mfma_f32_32x32x16_f16 v[16:31], v[34:37], v[174:177], 0
	v_mfma_f32_32x32x16_f16 v[16:31], v[38:41], v[170:173], v[16:31]
	v_mfma_f32_32x32x16_f16 v[16:31], v[42:45], v[166:169], v[16:31]
	s_nop 8
	v_max_i32_e32 v0, 0, v0
	v_max_i32_e32 v1, 0, v1
	v_fma_f32 v240, v0, v114, 0
	v_fma_f32 v241, v1, v115, 0
	v_max_i32_e32 v2, 0, v2
	v_max_i32_e32 v3, 0, v3
	v_fma_f32 v240, v2, v116, v240
	v_mfma_f32_32x32x16_f16 v[16:31], v[46:49], v[162:165], v[16:31]
	v_fma_f32 v241, v3, v117, v241
	v_max_i32_e32 v4, 0, v4
	v_max_i32_e32 v5, 0, v5
	v_fma_f32 v240, v4, v118, v240
	v_fma_f32 v241, v5, v119, v241
	v_max_i32_e32 v6, 0, v6
	v_max_i32_e32 v7, 0, v7
	v_mfma_f32_32x32x16_f16 v[16:31], v[50:53], v[158:161], v[16:31]
	v_fma_f32 v240, v6, v120, v240
	v_fma_f32 v241, v7, v121, v241
	v_max_i32_e32 v8, 0, v8
	v_max_i32_e32 v9, 0, v9
	v_fma_f32 v240, v8, v122, v240
	v_fma_f32 v241, v9, v123, v241
	v_mfma_f32_32x32x16_f16 v[16:31], v[54:57], v[154:157], v[16:31]
	v_max_i32_e32 v10, 0, v10
	v_max_i32_e32 v11, 0, v11
	v_fma_f32 v240, v10, v124, v240
	v_fma_f32 v241, v11, v125, v241
	v_max_i32_e32 v12, 0, v12
	v_max_i32_e32 v13, 0, v13
	v_mfma_f32_32x32x16_f16 v[16:31], v[58:61], v[150:153], v[16:31]
	v_fma_f32 v240, v12, v126, v240
	v_fma_f32 v241, v13, v127, v241
	v_max_i32_e32 v14, 0, v14
	v_max_i32_e32 v15, 0, v15
	v_fma_f32 v240, v14, v128, v240
	v_fma_f32 v241, v15, v129, v241
	v_mfma_f32_32x32x16_f16 v[16:31], v[62:65], v[146:149], v[16:31]
	v_add_f32_e32 v242, v238, v239
	v_add_f32_e32 v243, v240, v241
	v_lshl_add_u32 v244, v32, 2, v248
	s_nop 0
	v_permlane32_swap_b32_e32 v242, v243
	v_add_f32_e32 v242, v242, v243
	global_store_dword v244, v242, s[6:7]
	v_mfma_f32_32x32x16_f16 v[0:15], v[82:85], v[174:177], 0
	v_mfma_f32_32x32x16_f16 v[0:15], v[86:89], v[170:173], v[0:15]
	v_mfma_f32_32x32x16_f16 v[0:15], v[90:93], v[166:169], v[0:15]
	s_nop 8
	v_max_i32_e32 v16, 0, v16
	v_max_i32_e32 v17, 0, v17
	v_fma_f32 v238, v16, v66, 0
	v_fma_f32 v239, v17, v67, 0
	v_max_i32_e32 v18, 0, v18
	v_max_i32_e32 v19, 0, v19
	v_fma_f32 v238, v18, v68, v238
	v_mfma_f32_32x32x16_f16 v[0:15], v[94:97], v[162:165], v[0:15]
	v_fma_f32 v239, v19, v69, v239
	v_max_i32_e32 v20, 0, v20
	v_max_i32_e32 v21, 0, v21
	v_fma_f32 v238, v20, v70, v238
	v_fma_f32 v239, v21, v71, v239
	v_max_i32_e32 v22, 0, v22
	v_max_i32_e32 v23, 0, v23
	v_mfma_f32_32x32x16_f16 v[0:15], v[98:101], v[158:161], v[0:15]
	v_fma_f32 v238, v22, v72, v238
	v_fma_f32 v239, v23, v73, v239
	v_max_i32_e32 v24, 0, v24
	v_max_i32_e32 v25, 0, v25
	v_fma_f32 v238, v24, v74, v238
	v_fma_f32 v239, v25, v75, v239
	v_mfma_f32_32x32x16_f16 v[0:15], v[102:105], v[154:157], v[0:15]
	v_max_i32_e32 v26, 0, v26
	v_max_i32_e32 v27, 0, v27
	v_fma_f32 v238, v26, v76, v238
	v_fma_f32 v239, v27, v77, v239
	v_max_i32_e32 v28, 0, v28
	v_max_i32_e32 v29, 0, v29
	v_mfma_f32_32x32x16_f16 v[0:15], v[106:109], v[150:153], v[0:15]
	v_fma_f32 v238, v28, v78, v238
	v_fma_f32 v239, v29, v79, v239
	v_max_i32_e32 v30, 0, v30
	v_max_i32_e32 v31, 0, v31
	v_fma_f32 v238, v30, v80, v238
	v_fma_f32 v239, v31, v81, v239
	v_mfma_f32_32x32x16_f16 v[0:15], v[110:113], v[146:149], v[0:15]
	s_nop 11
	v_max_i32_e32 v0, 0, v0
	v_max_i32_e32 v1, 0, v1
	v_fma_f32 v240, v0, v114, 0
	v_fma_f32 v241, v1, v115, 0
	v_max_i32_e32 v2, 0, v2
	v_max_i32_e32 v3, 0, v3
	v_fma_f32 v240, v2, v116, v240
	v_fma_f32 v241, v3, v117, v241
	v_max_i32_e32 v4, 0, v4
	v_max_i32_e32 v5, 0, v5
	v_fma_f32 v240, v4, v118, v240
	v_fma_f32 v241, v5, v119, v241
	v_max_i32_e32 v6, 0, v6
	v_max_i32_e32 v7, 0, v7
	v_fma_f32 v240, v6, v120, v240
	v_fma_f32 v241, v7, v121, v241
	v_max_i32_e32 v8, 0, v8
	v_max_i32_e32 v9, 0, v9
	v_fma_f32 v240, v8, v122, v240
	v_fma_f32 v241, v9, v123, v241
	v_max_i32_e32 v10, 0, v10
	v_max_i32_e32 v11, 0, v11
	v_fma_f32 v240, v10, v124, v240
	v_fma_f32 v241, v11, v125, v241
	v_max_i32_e32 v12, 0, v12
	v_max_i32_e32 v13, 0, v13
	v_fma_f32 v240, v12, v126, v240
	v_fma_f32 v241, v13, v127, v241
	v_max_i32_e32 v14, 0, v14
	v_max_i32_e32 v15, 0, v15
	v_fma_f32 v240, v14, v128, v240
	v_fma_f32 v241, v15, v129, v241
	v_add_f32_e32 v242, v238, v239
	v_add_f32_e32 v243, v240, v241
	v_lshl_add_u32 v244, v32, 2, v248
	s_nop 0
	v_permlane32_swap_b32_e32 v242, v243
	v_add_f32_e32 v242, v242, v243
	global_store_dword v244, v242, s[6:7] offset:128
	s_add_i32 s18, s14, -3
	s_cmp_lt_u32 s18, s42
	s_cselect_b64 s[12:13], -1, 0
	s_cmp_ge_u32 s18, s42
	s_cbranch_scc1 .LBB0_1897
	s_waitcnt vmcnt(4)
	ds_write_b128 v209, v[134:137] offset:17408
	ds_write_b128 v209, v[142:145] offset:26112

; #define LAS __attribute__((address_space(3)))
; DI void indexer_tile(const LAS unsigned char* buf, const f16x8 (&af)[2][8], const f32x4 (&wv)[2][4], float* sc0, float* sc1, int kt, int r32, int h2) {
;     typedef float f32x2_t __attribute__((ext_vector_type(2)));
;     f16x8 bfr[2][8];
; #pragma unroll
;     for (int sub = 0; sub < 2; ++sub)
; #pragma unroll
;         for (int ks = 0; ks < 8; ++ks) bfr[sub][ks] = *(const LAS f16x8*)(buf + (32 * sub + r32) * KT_ROWB + (16 * ks + 8 * h2) * 2);
;     __builtin_amdgcn_sched_barrier(0);
; #pragma unroll
;     for (int sub = 0; sub < 2; ++sub) {
;         f32x16 c0, c1;
; #pragma unroll
;         for (int i = 0; i < 16; ++i) { c0[i] = 0.f; c1[i] = 0.f; }
; #pragma unroll
;         for (int ks = 0; ks < 8; ++ks) { c0 = __builtin_amdgcn_mfma_f32_32x32x16_f16(af[0][ks], bfr[sub][ks], c0, 0, 0, 0); c1 = __builtin_amdgcn_mfma_f32_32x32x16_f16(af[1][ks], bfr[sub][ks], c1, 0, 0, 0); }
;         f32x2_t a0 = {0.f, 0.f}, a1 = {0.f, 0.f};
; #pragma unroll
;         for (int q = 0; q < 4; ++q)
; #pragma unroll
;             for (int e = 0; e < 4; e += 2) {
;                 const f32x2_t r0 = {relu1(c0[4 * q + e]), relu1(c0[4 * q + e + 1])};
;                 const f32x2_t r1 = {relu1(c1[4 * q + e]), relu1(c1[4 * q + e + 1])};
;                 const f32x2_t w0 = {wv[0][q][e], wv[0][q][e + 1]}, w1 = {wv[1][q][e], wv[1][q][e + 1]};
;                 a0 = __builtin_elementwise_fma(r0, w0, a0); a1 = __builtin_elementwise_fma(r1, w1, a1); }
;         float s0 = a0.x + a0.y, s1 = a1.x + a1.y;
;         s0 += __shfl_xor(s0, 32); s1 += __shfl_xor(s1, 32);
;         if (h2 == 0) { sc0[kt * 64 + 32 * sub + r32] = s0; sc1[kt * 64 + 32 * sub + r32] = s1; }
.LBB0_1900:
	ds_read_b128 v[0:3], v207 offset:17408
	ds_read_b128 v[210:213], v207 offset:17440
	ds_read_b128 v[214:217], v207 offset:17472
	ds_read_b128 v[218:221], v207 offset:17504
	ds_read_b128 v[222:225], v207 offset:17536
	ds_read_b128 v[226:229], v207 offset:17568
	ds_read_b128 v[230:233], v207 offset:17600
	ds_read_b128 v[234:237], v207 offset:17632
	ds_read_b128 v[174:177], v207 offset:26112
	ds_read_b128 v[170:173], v207 offset:26144
	ds_read_b128 v[166:169], v207 offset:26176
	ds_read_b128 v[162:165], v207 offset:26208
	ds_read_b128 v[158:161], v207 offset:26240
	ds_read_b128 v[154:157], v207 offset:26272
	ds_read_b128 v[150:153], v207 offset:26304
	ds_read_b128 v[146:149], v207 offset:26336
	s_waitcnt lgkmcnt(15)
	v_mfma_f32_32x32x16_f16 v[16:31], v[34:37], v[0:3], 0
	s_waitcnt lgkmcnt(14)
	v_mfma_f32_32x32x16_f16 v[16:31], v[38:41], v[210:213], v[16:31]
	s_waitcnt lgkmcnt(13)
	v_mfma_f32_32x32x16_f16 v[16:31], v[42:45], v[214:217], v[16:31]
	s_waitcnt lgkmcnt(12)
	v_mfma_f32_32x32x16_f16 v[16:31], v[46:49], v[218:221], v[16:31]
	s_waitcnt lgkmcnt(11)
	v_mfma_f32_32x32x16_f16 v[16:31], v[50:53], v[222:225], v[16:31]
	s_waitcnt lgkmcnt(10)
	v_mfma_f32_32x32x16_f16 v[16:31], v[54:57], v[226:229], v[16:31]
	s_waitcnt lgkmcnt(9)
	v_mfma_f32_32x32x16_f16 v[16:31], v[58:61], v[230:233], v[16:31]
	s_waitcnt lgkmcnt(8)
	v_mfma_f32_32x32x16_f16 v[16:31], v[62:65], v[234:237], v[16:31]
	v_mfma_f32_32x32x16_f16 v[0:15], v[82:85], v[0:3], 0
	v_mfma_f32_32x32x16_f16 v[0:15], v[86:89], v[210:213], v[0:15]
	v_mfma_f32_32x32x16_f16 v[0:15], v[90:93], v[214:217], v[0:15]
	s_nop 8
	v_max_i32_e32 v16, 0, v16
	v_max_i32_e32 v17, 0, v17
	v_fma_f32 v238, v16, v66, 0
	v_fma_f32 v239, v17, v67, 0
	v_max_i32_e32 v18, 0, v18
	v_max_i32_e32 v19, 0, v19
	v_fma_f32 v238, v18, v68, v238
	v_mfma_f32_32x32x16_f16 v[0:15], v[94:97], v[218:221], v[0:15]
	v_fma_f32 v239, v19, v69, v239
	v_max_i32_e32 v20, 0, v20
	v_max_i32_e32 v21, 0, v21
	v_fma_f32 v238, v20, v70, v238
	v_fma_f32 v239, v21, v71, v239
	v_max_i32_e32 v22, 0, v22
	v_max_i32_e32 v23, 0, v23
	v_mfma_f32_32x32x16_f16 v[0:15], v[98:101], v[222:225], v[0:15]
	v_fma_f32 v238, v22, v72, v238
	v_fma_f32 v239, v23, v73, v239
	v_max_i32_e32 v24, 0, v24
	v_max_i32_e32 v25, 0, v25
	v_fma_f32 v238, v24, v74, v238
	v_fma_f32 v239, v25, v75, v239
	v_mfma_f32_32x32x16_f16 v[0:15], v[102:105], v[226:229], v[0:15]
	v_max_i32_e32 v26, 0, v26
	v_max_i32_e32 v27, 0, v27
	v_fma_f32 v238, v26, v76, v238
	v_fma_f32 v239, v27, v77, v239
	v_max_i32_e32 v28, 0, v28
	v_max_i32_e32 v29, 0, v29
	v_mfma_f32_32x32x16_f16 v[0:15], v[106:109], v[230:233], v[0:15]
	v_fma_f32 v238, v28, v78, v238
	v_fma_f32 v239, v29, v79, v239
	v_max_i32_e32 v30, 0, v30
	v_max_i32_e32 v31, 0, v31
	v_fma_f32 v238, v30, v80, v238
	v_fma_f32 v239, v31, v81, v239
	v_mfma_f32_32x32x16_f16 v[0:15], v[110:113], v[234:237], v[0:15]
	s_waitcnt lgkmcnt(0)
; #define LAS __attribute__((address_space(3)))
; DI void indexer_tile(const LAS unsigned char* buf, const f16x8 (&af)[2][8], const f32x4 (&wv)[2][4], float* sc0, float* sc1, int kt, int r32, int h2) {
;     ...
;     for (int sub = 0; sub < 2; ++sub) {
;         f32x16 c0, c1;
; #pragma unroll
;         for (int i = 0; i < 16; ++i) { c0[i] = 0.f; c1[i] = 0.f; }
; #pragma unroll
;         for (int ks = 0; ks < 8; ++ks) { c0 = __builtin_amdgcn_mfma_f32_32x32x16_f16(af[0][ks], bfr[sub][ks], c0, 0, 0, 0); c1 = __builtin_amdgcn_mfma_f32_32x32x16_f16(af[1][ks], bfr[sub][ks], c1, 0, 0, 0); }
;         f32x2_t a0 = {0.f, 0.f}, a1 = {0.f, 0.f};
; #pragma unroll
;         for (int q = 0; q < 4; ++q)
; #pragma unroll
;             for (int e = 0; e < 4; e += 2) {
;                 const f32x2_t r0 = {relu1(c0[4 * q + e]), relu1(c0[4 * q + e + 1])};
;                 const f32x2_t r1 = {relu1(c1[4 * q + e]), relu1(c1[4 * q + e + 1])};
;                 const f32x2_t w0 = {wv[0][q][e], wv[0][q][e + 1]}, w1 = {wv[1][q][e], wv[1][q][e + 1]};
;                 a0 = __builtin_elementwise_fma(r0, w0, a0); a1 = __builtin_elementwise_fma(r1, w1, a1); }
;         float s0 = a0.x + a0.y, s1 = a1.x + a1.y;
;         s0 += __shfl_xor(s0, 32); s1 += __shfl_xor(s1, 32);
;         if (h2 == 0) { sc0[kt * 64 + 32 * sub + r32] = s0; sc1[kt * 64 + 32 * sub + r32] = s1; }
; DI void indexer_phase(const unsigned short* QI, const unsigned short* KI16, const float* WI, float* SC, LAS unsigned char* lds, int tid, int bid, int G) {
;     ...
;                 if (kt + 2 < nt) { *(LAS u32x4*)(buf0 + key0 * KT_ROWB + ch * 16) = a0; *(LAS u32x4*)(buf0 + (key0 + 32) * KT_ROWB + ch * 16) = a1; }
	v_mfma_f32_32x32x16_f16 v[16:31], v[34:37], v[174:177], 0
	v_mfma_f32_32x32x16_f16 v[16:31], v[38:41], v[170:173], v[16:31]
	v_mfma_f32_32x32x16_f16 v[16:31], v[42:45], v[166:169], v[16:31]
	s_nop 8
	v_max_i32_e32 v0, 0, v0
	v_max_i32_e32 v1, 0, v1
	v_fma_f32 v240, v0, v114, 0
	v_fma_f32 v241, v1, v115, 0
	v_max_i32_e32 v2, 0, v2
	v_max_i32_e32 v3, 0, v3
	v_fma_f32 v240, v2, v116, v240
	v_mfma_f32_32x32x16_f16 v[16:31], v[46:49], v[162:165], v[16:31]
	v_fma_f32 v241, v3, v117, v241
	v_max_i32_e32 v4, 0, v4
	v_max_i32_e32 v5, 0, v5
	v_fma_f32 v240, v4, v118, v240
	v_fma_f32 v241, v5, v119, v241
	v_max_i32_e32 v6, 0, v6
	v_max_i32_e32 v7, 0, v7
	v_mfma_f32_32x32x16_f16 v[16:31], v[50:53], v[158:161], v[16:31]
	v_fma_f32 v240, v6, v120, v240
	v_fma_f32 v241, v7, v121, v241
	v_max_i32_e32 v8, 0, v8
	v_max_i32_e32 v9, 0, v9
	v_fma_f32 v240, v8, v122, v240
	v_fma_f32 v241, v9, v123, v241
	v_mfma_f32_32x32x16_f16 v[16:31], v[54:57], v[154:157], v[16:31]
	v_max_i32_e32 v10, 0, v10
	v_max_i32_e32 v11, 0, v11
	v_fma_f32 v240, v10, v124, v240
	v_fma_f32 v241, v11, v125, v241
	v_max_i32_e32 v12, 0, v12
	v_max_i32_e32 v13, 0, v13
	v_mfma_f32_32x32x16_f16 v[16:31], v[58:61], v[150:153], v[16:31]
	v_fma_f32 v240, v12, v126, v240
	v_fma_f32 v241, v13, v127, v241
	v_max_i32_e32 v14, 0, v14
	v_max_i32_e32 v15, 0, v15
	v_fma_f32 v240, v14, v128, v240
	v_fma_f32 v241, v15, v129, v241
	v_mfma_f32_32x32x16_f16 v[16:31], v[62:65], v[146:149], v[16:31]
	v_add_f32_e32 v242, v238, v239
	v_add_f32_e32 v243, v240, v241
	v_lshl_add_u32 v244, v32, 2, v248
	s_nop 0
	v_permlane32_swap_b32_e32 v242, v243
	v_add_f32_e32 v242, v242, v243
	global_store_dword v244, v242, s[6:7] offset:256
	v_mfma_f32_32x32x16_f16 v[0:15], v[82:85], v[174:177], 0
	v_mfma_f32_32x32x16_f16 v[0:15], v[86:89], v[170:173], v[0:15]
	v_mfma_f32_32x32x16_f16 v[0:15], v[90:93], v[166:169], v[0:15]
	s_nop 8
	v_max_i32_e32 v16, 0, v16
	v_max_i32_e32 v17, 0, v17
	v_fma_f32 v238, v16, v66, 0
	v_fma_f32 v239, v17, v67, 0
	v_max_i32_e32 v18, 0, v18
	v_max_i32_e32 v19, 0, v19
	v_fma_f32 v238, v18, v68, v238
	v_mfma_f32_32x32x16_f16 v[0:15], v[94:97], v[162:165], v[0:15]
	v_fma_f32 v239, v19, v69, v239
	v_max_i32_e32 v20, 0, v20
	v_max_i32_e32 v21, 0, v21
	v_fma_f32 v238, v20, v70, v238
	v_fma_f32 v239, v21, v71, v239
	v_max_i32_e32 v22, 0, v22
	v_max_i32_e32 v23, 0, v23
	v_mfma_f32_32x32x16_f16 v[0:15], v[98:101], v[158:161], v[0:15]
	v_fma_f32 v238, v22, v72, v238
	v_fma_f32 v239, v23, v73, v239
	v_max_i32_e32 v24, 0, v24
	v_max_i32_e32 v25, 0, v25
	v_fma_f32 v238, v24, v74, v238
	v_fma_f32 v239, v25, v75, v239
	v_mfma_f32_32x32x16_f16 v[0:15], v[102:105], v[154:157], v[0:15]
	v_max_i32_e32 v26, 0, v26
	v_max_i32_e32 v27, 0, v27
	v_fma_f32 v238, v26, v76, v238
	v_fma_f32 v239, v27, v77, v239
	v_max_i32_e32 v28, 0, v28
	v_max_i32_e32 v29, 0, v29
	v_mfma_f32_32x32x16_f16 v[0:15], v[106:109], v[150:153], v[0:15]
	v_fma_f32 v238, v28, v78, v238
	v_fma_f32 v239, v29, v79, v239
	v_max_i32_e32 v30, 0, v30
	v_max_i32_e32 v31, 0, v31
	v_fma_f32 v238, v30, v80, v238
	v_fma_f32 v239, v31, v81, v239
	v_mfma_f32_32x32x16_f16 v[0:15], v[110:113], v[146:149], v[0:15]
	s_nop 11
	v_max_i32_e32 v0, 0, v0
	v_max_i32_e32 v1, 0, v1
	v_fma_f32 v240, v0, v114, 0
	v_fma_f32 v241, v1, v115, 0
	v_max_i32_e32 v2, 0, v2
	v_max_i32_e32 v3, 0, v3
	v_fma_f32 v240, v2, v116, v240
	v_fma_f32 v241, v3, v117, v241
	v_max_i32_e32 v4, 0, v4
	v_max_i32_e32 v5, 0, v5
	v_fma_f32 v240, v4, v118, v240
	v_fma_f32 v241, v5, v119, v241
	v_max_i32_e32 v6, 0, v6
	v_max_i32_e32 v7, 0, v7
	v_fma_f32 v240, v6, v120, v240
	v_fma_f32 v241, v7, v121, v241
	v_max_i32_e32 v8, 0, v8
	v_max_i32_e32 v9, 0, v9
	v_fma_f32 v240, v8, v122, v240
	v_fma_f32 v241, v9, v123, v241
	v_max_i32_e32 v10, 0, v10
	v_max_i32_e32 v11, 0, v11
	v_fma_f32 v240, v10, v124, v240
	v_fma_f32 v241, v11, v125, v241
	v_max_i32_e32 v12, 0, v12
	v_max_i32_e32 v13, 0, v13
	v_fma_f32 v240, v12, v126, v240
	v_fma_f32 v241, v13, v127, v241
	v_max_i32_e32 v14, 0, v14
	v_max_i32_e32 v15, 0, v15
	v_fma_f32 v240, v14, v128, v240
	v_fma_f32 v241, v15, v129, v241
	v_add_f32_e32 v242, v238, v239
	v_add_f32_e32 v243, v240, v241
	v_lshl_add_u32 v244, v32, 2, v248
	s_nop 0
	v_permlane32_swap_b32_e32 v242, v243
	v_add_f32_e32 v242, v242, v243
	global_store_dword v244, v242, s[6:7] offset:384
	s_andn2_b64 vcc, exec, s[10:11]
	s_cbranch_vccnz .LBB0_1888
	s_waitcnt vmcnt(4)
	ds_write_b128 v209, v[130:133]
	ds_write_b128 v209, v[138:141] offset:8704
	s_branch .LBB0_1888
